# write-through (sc1) stores for the inter-phase activations (GEMM epilogue outputs, row-prep h) so the grid barrier's L2 write-back has little left to flush
# speedup vs baseline: 1.0345x; 1.0042x over previous
; #define PG8_STAGE(bufoff, gbase, voff) do { _Pragma("unroll") for (int _i = 0; _i < 2; ++_i) \
;         __builtin_amdgcn_global_load_lds((const unsigned*)((const char*)(gbase) + (voff)[_i]), (PG8_LAS unsigned*)(lds + (bufoff) + ldsw + _i * 8192), 16, 0, 0); } while (0)
; #define PG8_LDA(dst, b, h) do { _Pragma("unroll") for (int m = 0; m < 4; ++m) _Pragma("unroll") for (int k = 0; k < 2; ++k) dst[m][k] = *(const PG8_LAS bf16x8*)(lds + PG8_SA(b, h) + aoff + m * 2048 + k * 1024); } while (0)
; #define PG8_LDB(dst, b, h) do { _Pragma("unroll") for (int n = 0; n < 2; ++n) _Pragma("unroll") for (int k = 0; k < 2; ++k) dst[n][k] = *(const PG8_LAS bf16x8*)(lds + PG8_SB(b, h) + boff + n * 2048 + k * 1024); } while (0)
; #define PG8_WAIT_V(n) asm volatile("s_waitcnt vmcnt(" #n ")" ::: "memory")
; #define PG8_WAIT_L(n) asm volatile("s_waitcnt lgkmcnt(" #n ")" ::: "memory")
; #define PG8_BAR __builtin_amdgcn_s_barrier()
; #define PG8_SCHED __builtin_amdgcn_sched_barrier(0)
; template <class Epi, class Sched>
; __device__ __forceinline__ void gemm_phase(PG8_LAS unsigned char* lds, const Gemm g, const Sched& S, const Epi& E) {
;     ...
;         for (int t = 0; t < nt; t += 2) {
;             const bool last = (t == nt - 2);
;             const char* a1 = cA + (size_t)(t + 1) * kstep;
;             const char* a2 = last ? nA : cA + (size_t)(t + 2) * kstep; const char* b2 = last ? nB : cB + (size_t)(t + 2) * kstep;
;             const char* a3 = a2 + kstep; const char* b3 = b2 + kstep;
;             if (last && has_next) S.a_ready(nxt);
;             PG8_LDB(B0, 0, 0); PG8_SCHED; PG8_LDA(At, 0, 0); PG8_STAGE(PG8_SA(1, 1), a1 + hstep, voffA);
;             PG8_WAIT_L(8); PG8_BAR; PG8_WAIT_L(0); PG8_MMA(0, 0, At, B0); PG8_BAR; PG8_SCHED;
;             PG8_LDB(B1, 0, 1); PG8_STAGE(PG8_SB(0, 0), b2, voffB);
;             PG8_BAR; PG8_WAIT_L(0); PG8_MMA(0, 1, At, B1); PG8_BAR;
;             PG8_LDA(At, 0, 1); PG8_STAGE(PG8_SA(0, 0), a2, voffA);
;             PG8_BAR; PG8_WAIT_L(0); PG8_MMA(1, 0, At, B0); PG8_BAR; PG8_SCHED;
;             PG8_STAGE(PG8_SB(0, 1), b2 + hstep, voffB);
;             PG8_WAIT_V(6); PG8_BAR; PG8_MMA(1, 1, At, B1); PG8_BAR;
;             PG8_LDB(B0, 1, 0); PG8_SCHED; PG8_LDA(At, 1, 0); PG8_STAGE(PG8_SA(0, 1), a2 + hstep, voffA);
;             PG8_WAIT_L(8); PG8_BAR; PG8_WAIT_L(0); PG8_MMA(0, 0, At, B0); PG8_BAR; PG8_SCHED;
.LBB0_96:
	s_add_u32 s10, s8, 0x100
	s_addc_u32 s11, s9, 0
	v_add_u32_e32 v154, 0x10000, v139
	ds_read_b128 v[142:145], v154
	ds_read_b128 v[146:149], v154 offset:1024
	ds_read_b128 v[150:153], v154 offset:2048
	ds_read_b128 v[154:157], v154 offset:3072
	s_cmp_eq_u32 s45, 40
	s_cselect_b32 s15, s1, s11
	s_cselect_b32 s14, s0, s10
	s_cselect_b32 s13, s5, s44
	s_cselect_b32 s12, s4, s43
	s_add_i32 m0, s20, 0xc000
	ds_read_b128 v[158:161], v141
	ds_read_b128 v[162:165], v141 offset:1024
	ds_read_b128 v[166:169], v141 offset:2048
	ds_read_b128 v[170:173], v141 offset:3072
	ds_read_b128 v[178:181], v141 offset:4096
	ds_read_b128 v[182:185], v141 offset:5120
	ds_read_b128 v[186:189], v141 offset:6144
	global_load_lds_dwordx4 v134, s[8:9]
	s_add_i32 m0, s20, 0xe000
	ds_read_b128 v[190:193], v141 offset:7168
	global_load_lds_dwordx4 v136, s[8:9]
	s_waitcnt lgkmcnt(8)
	s_barrier
	s_waitcnt lgkmcnt(7)
	v_mfma_f32_16x16x32_bf16 v[124:127], v[142:145], v[158:161], v[124:127]
	v_mfma_f32_16x16x32_bf16 v[120:123], v[150:153], v[158:161], v[120:123]
	s_waitcnt lgkmcnt(5)
	v_mfma_f32_16x16x32_bf16 v[116:119], v[142:145], v[166:169], v[116:119]
	v_mfma_f32_16x16x32_bf16 v[112:115], v[150:153], v[166:169], v[112:115]
	s_waitcnt lgkmcnt(3)
	v_mfma_f32_16x16x32_bf16 v[100:103], v[142:145], v[178:181], v[100:103]
	v_mfma_f32_16x16x32_bf16 v[96:99], v[150:153], v[178:181], v[96:99]
	s_waitcnt lgkmcnt(1)
	v_mfma_f32_16x16x32_bf16 v[84:87], v[142:145], v[186:189], v[84:87]
	v_mfma_f32_16x16x32_bf16 v[80:83], v[150:153], v[186:189], v[80:83]
	v_mfma_f32_16x16x32_bf16 v[124:127], v[146:149], v[162:165], v[124:127]
	v_mfma_f32_16x16x32_bf16 v[120:123], v[154:157], v[162:165], v[120:123]
	v_mfma_f32_16x16x32_bf16 v[116:119], v[146:149], v[170:173], v[116:119]
	v_mfma_f32_16x16x32_bf16 v[112:115], v[154:157], v[170:173], v[112:115]
	v_mfma_f32_16x16x32_bf16 v[100:103], v[146:149], v[182:185], v[100:103]
	v_mfma_f32_16x16x32_bf16 v[96:99], v[154:157], v[182:185], v[96:99]
	s_waitcnt lgkmcnt(0)
	v_mfma_f32_16x16x32_bf16 v[84:87], v[146:149], v[190:193], v[84:87]
	v_mfma_f32_16x16x32_bf16 v[80:83], v[154:157], v[190:193], v[80:83]
	s_barrier
	s_add_i32 s47, 0, 0x14000
	v_add_u32_e32 v174, 0x14000, v139
	ds_read_b128 v[194:197], v174
	ds_read_b128 v[198:201], v174 offset:1024
	s_add_u32 s98, s12, 0x80
	s_addc_u32 s99, s13, 0
	s_add_i32 m0, s18, 0x10000
	ds_read_b128 v[202:205], v174 offset:2048
	global_load_lds_dwordx4 v176, s[12:13]
	s_add_i32 m0, s18, 0x12000
	ds_read_b128 v[206:209], v174 offset:3072
	global_load_lds_dwordx4 v128, s[12:13]
	s_barrier
	s_waitcnt lgkmcnt(3)
	v_mfma_f32_16x16x32_bf16 v[108:111], v[194:197], v[158:161], v[108:111]
	s_waitcnt lgkmcnt(1)
	v_mfma_f32_16x16x32_bf16 v[104:107], v[202:205], v[158:161], v[104:107]
	v_mfma_f32_16x16x32_bf16 v[92:95], v[194:197], v[166:169], v[92:95]
	v_mfma_f32_16x16x32_bf16 v[88:91], v[202:205], v[166:169], v[88:91]
	v_mfma_f32_16x16x32_bf16 v[76:79], v[194:197], v[178:181], v[76:79]
	v_mfma_f32_16x16x32_bf16 v[72:75], v[202:205], v[178:181], v[72:75]
	v_mfma_f32_16x16x32_bf16 v[68:71], v[194:197], v[186:189], v[68:71]
	v_mfma_f32_16x16x32_bf16 v[64:67], v[202:205], v[186:189], v[64:67]
	v_mfma_f32_16x16x32_bf16 v[108:111], v[198:201], v[162:165], v[108:111]
	s_waitcnt lgkmcnt(0)
	v_mfma_f32_16x16x32_bf16 v[104:107], v[206:209], v[162:165], v[104:107]
	v_mfma_f32_16x16x32_bf16 v[92:95], v[198:201], v[170:173], v[92:95]
	v_mfma_f32_16x16x32_bf16 v[88:91], v[206:209], v[170:173], v[88:91]
	v_mfma_f32_16x16x32_bf16 v[76:79], v[198:201], v[182:185], v[76:79]
	v_mfma_f32_16x16x32_bf16 v[72:75], v[206:209], v[182:185], v[72:75]
	v_mfma_f32_16x16x32_bf16 v[68:71], v[198:201], v[190:193], v[68:71]
	v_mfma_f32_16x16x32_bf16 v[64:67], v[206:209], v[190:193], v[64:67]
	s_mov_b32 m0, s20
	s_add_u32 s100, s14, 0x80
	s_addc_u32 s101, s15, 0
	s_barrier
	ds_read_b128 v[158:161], v141 offset:16384
	ds_read_b128 v[162:165], v141 offset:17408
	ds_read_b128 v[166:169], v141 offset:18432
	ds_read_b128 v[170:173], v141 offset:19456
	ds_read_b128 v[178:181], v141 offset:20480
	ds_read_b128 v[182:185], v141 offset:21504
	ds_read_b128 v[186:189], v141 offset:22528
	global_load_lds_dwordx4 v132, s[14:15]
	s_mov_b32 m0, s21
	ds_read_b128 v[190:193], v141 offset:23552
	global_load_lds_dwordx4 v130, s[14:15]
	s_barrier
	s_waitcnt lgkmcnt(7)
	v_mfma_f32_16x16x32_bf16 v[60:63], v[142:145], v[158:161], v[60:63]
	v_mfma_f32_16x16x32_bf16 v[56:59], v[150:153], v[158:161], v[56:59]
	s_waitcnt lgkmcnt(5)
	v_mfma_f32_16x16x32_bf16 v[52:55], v[142:145], v[166:169], v[52:55]
	v_mfma_f32_16x16x32_bf16 v[48:51], v[150:153], v[166:169], v[48:51]
	s_waitcnt lgkmcnt(3)
	v_mfma_f32_16x16x32_bf16 v[36:39], v[142:145], v[178:181], v[36:39]
	v_mfma_f32_16x16x32_bf16 v[32:35], v[150:153], v[178:181], v[32:35]
	s_waitcnt lgkmcnt(1)
	v_mfma_f32_16x16x32_bf16 v[20:23], v[142:145], v[186:189], v[20:23]
	v_mfma_f32_16x16x32_bf16 v[16:19], v[150:153], v[186:189], v[16:19]
	v_mfma_f32_16x16x32_bf16 v[60:63], v[146:149], v[162:165], v[60:63]
	v_mfma_f32_16x16x32_bf16 v[56:59], v[154:157], v[162:165], v[56:59]
	v_mfma_f32_16x16x32_bf16 v[52:55], v[146:149], v[170:173], v[52:55]
	v_mfma_f32_16x16x32_bf16 v[48:51], v[154:157], v[170:173], v[48:51]
	v_mfma_f32_16x16x32_bf16 v[36:39], v[146:149], v[182:185], v[36:39]
	v_mfma_f32_16x16x32_bf16 v[32:35], v[154:157], v[182:185], v[32:35]
	s_waitcnt lgkmcnt(0)
	v_mfma_f32_16x16x32_bf16 v[20:23], v[146:149], v[190:193], v[20:23]
	v_mfma_f32_16x16x32_bf16 v[16:19], v[154:157], v[190:193], v[16:19]
	s_barrier
	s_add_u32 s8, s12, 0xb0000
	s_addc_u32 s9, s13, 0
	s_add_i32 m0, s18, 0x14000
	s_nop 0
	global_load_lds_dwordx4 v176, s[8:9]
	s_add_i32 m0, s18, 0x16000
	s_nop 0
	global_load_lds_dwordx4 v128, s[8:9]
	s_waitcnt vmcnt(6)
	s_barrier
; #define PG8_STAGE(bufoff, gbase, voff) do { _Pragma("unroll") for (int _i = 0; _i < 2; ++_i) \
;         __builtin_amdgcn_global_load_lds((const unsigned*)((const char*)(gbase) + (voff)[_i]), (PG8_LAS unsigned*)(lds + (bufoff) + ldsw + _i * 8192), 16, 0, 0); } while (0)
; #define PG8_LDA(dst, b, h) do { _Pragma("unroll") for (int m = 0; m < 4; ++m) _Pragma("unroll") for (int k = 0; k < 2; ++k) dst[m][k] = *(const PG8_LAS bf16x8*)(lds + PG8_SA(b, h) + aoff + m * 2048 + k * 1024); } while (0)
; #define PG8_LDB(dst, b, h) do { _Pragma("unroll") for (int n = 0; n < 2; ++n) _Pragma("unroll") for (int k = 0; k < 2; ++k) dst[n][k] = *(const PG8_LAS bf16x8*)(lds + PG8_SB(b, h) + boff + n * 2048 + k * 1024); } while (0)
; #define PG8_MMA(ai, bj, At, Bt) do { __builtin_amdgcn_s_setprio(1); _Pragma("unroll") for (int m = 0; m < 4; ++m) _Pragma("unroll") for (int n = 0; n < 2; ++n) _Pragma("unroll") for (int k = 0; k < 2; ++k) \
;         acc[ai][bj][m][n] = __builtin_amdgcn_mfma_f32_16x16x32_bf16(Bt[n][k], At[m][k], acc[ai][bj][m][n], 0, 0, 0); __builtin_amdgcn_s_setprio(0); } while (0)
; #define PG8_WAIT_V(n) asm volatile("s_waitcnt vmcnt(" #n ")" ::: "memory")
; #define PG8_WAIT_L(n) asm volatile("s_waitcnt lgkmcnt(" #n ")" ::: "memory")
; #define PG8_BAR __builtin_amdgcn_s_barrier()
; #define PG8_SCHED __builtin_amdgcn_sched_barrier(0)
; template <class Epi, class Sched>
; __device__ __forceinline__ void gemm_phase(PG8_LAS unsigned char* lds, const Gemm g, const Sched& S, const Epi& E) {
;     ...
;             PG8_WAIT_V(6); PG8_BAR; PG8_MMA(1, 1, At, B1); PG8_BAR;
;             PG8_LDB(B0, 1, 0); PG8_SCHED; PG8_LDA(At, 1, 0); PG8_STAGE(PG8_SA(0, 1), a2 + hstep, voffA);
;             PG8_WAIT_L(8); PG8_BAR; PG8_WAIT_L(0); PG8_MMA(0, 0, At, B0); PG8_BAR; PG8_SCHED;
;             PG8_LDB(B1, 1, 1); PG8_STAGE(PG8_SB(1, 0), b3, voffB);
;             PG8_BAR; PG8_WAIT_L(0); PG8_MMA(0, 1, At, B1); PG8_BAR;
;             PG8_LDA(At, 1, 1); PG8_STAGE(PG8_SA(1, 0), a3, voffA);
	v_mfma_f32_16x16x32_bf16 v[44:47], v[194:197], v[158:161], v[44:47]
	v_mfma_f32_16x16x32_bf16 v[40:43], v[202:205], v[158:161], v[40:43]
	v_mfma_f32_16x16x32_bf16 v[28:31], v[194:197], v[166:169], v[28:31]
	v_mfma_f32_16x16x32_bf16 v[24:27], v[202:205], v[166:169], v[24:27]
	v_mfma_f32_16x16x32_bf16 v[12:15], v[194:197], v[178:181], v[12:15]
	v_mfma_f32_16x16x32_bf16 v[8:11], v[202:205], v[178:181], v[8:11]
	v_mfma_f32_16x16x32_bf16 v[4:7], v[194:197], v[186:189], v[4:7]
	v_mfma_f32_16x16x32_bf16 v[0:3], v[202:205], v[186:189], v[0:3]
	v_mfma_f32_16x16x32_bf16 v[44:47], v[198:201], v[162:165], v[44:47]
	v_mfma_f32_16x16x32_bf16 v[40:43], v[206:209], v[162:165], v[40:43]
	v_mfma_f32_16x16x32_bf16 v[28:31], v[198:201], v[170:173], v[28:31]
	v_mfma_f32_16x16x32_bf16 v[24:27], v[206:209], v[170:173], v[24:27]
	v_mfma_f32_16x16x32_bf16 v[12:15], v[198:201], v[182:185], v[12:15]
	v_mfma_f32_16x16x32_bf16 v[8:11], v[206:209], v[182:185], v[8:11]
	v_mfma_f32_16x16x32_bf16 v[4:7], v[198:201], v[190:193], v[4:7]
	v_mfma_f32_16x16x32_bf16 v[0:3], v[206:209], v[190:193], v[0:3]
	s_add_i32 s46, 0, 0x18000
	v_add_u32_e32 v154, 0x18000, v139
	s_barrier
	ds_read_b128 v[142:145], v154
	ds_read_b128 v[146:149], v154 offset:1024
	ds_read_b128 v[150:153], v154 offset:2048
	ds_read_b128 v[154:157], v154 offset:3072
	s_add_u32 s8, s14, 0xb0000
	s_addc_u32 s9, s15, 0
	s_mov_b32 m0, s22
	ds_read_b128 v[158:161], v141 offset:32768
	ds_read_b128 v[162:165], v141 offset:33792
	ds_read_b128 v[166:169], v141 offset:34816
	ds_read_b128 v[170:173], v141 offset:35840
	ds_read_b128 v[178:181], v141 offset:36864
	ds_read_b128 v[182:185], v141 offset:37888
	ds_read_b128 v[186:189], v141 offset:38912
	global_load_lds_dwordx4 v132, s[8:9]
	s_mov_b32 m0, s23
	ds_read_b128 v[190:193], v141 offset:39936
	global_load_lds_dwordx4 v130, s[8:9]
	s_waitcnt lgkmcnt(8)
	s_barrier
	s_waitcnt lgkmcnt(7)
	v_mfma_f32_16x16x32_bf16 v[124:127], v[142:145], v[158:161], v[124:127]
	v_mfma_f32_16x16x32_bf16 v[120:123], v[150:153], v[158:161], v[120:123]
	s_waitcnt lgkmcnt(5)
	v_mfma_f32_16x16x32_bf16 v[116:119], v[142:145], v[166:169], v[116:119]
	v_mfma_f32_16x16x32_bf16 v[112:115], v[150:153], v[166:169], v[112:115]
	s_waitcnt lgkmcnt(3)
	v_mfma_f32_16x16x32_bf16 v[100:103], v[142:145], v[178:181], v[100:103]
	v_mfma_f32_16x16x32_bf16 v[96:99], v[150:153], v[178:181], v[96:99]
	s_waitcnt lgkmcnt(1)
	v_mfma_f32_16x16x32_bf16 v[84:87], v[142:145], v[186:189], v[84:87]
	v_mfma_f32_16x16x32_bf16 v[80:83], v[150:153], v[186:189], v[80:83]
	v_mfma_f32_16x16x32_bf16 v[124:127], v[146:149], v[162:165], v[124:127]
	v_mfma_f32_16x16x32_bf16 v[120:123], v[154:157], v[162:165], v[120:123]
	v_mfma_f32_16x16x32_bf16 v[116:119], v[146:149], v[170:173], v[116:119]
	v_mfma_f32_16x16x32_bf16 v[112:115], v[154:157], v[170:173], v[112:115]
	v_mfma_f32_16x16x32_bf16 v[100:103], v[146:149], v[182:185], v[100:103]
	v_mfma_f32_16x16x32_bf16 v[96:99], v[154:157], v[182:185], v[96:99]
	s_waitcnt lgkmcnt(0)
	v_mfma_f32_16x16x32_bf16 v[84:87], v[146:149], v[190:193], v[84:87]
	v_mfma_f32_16x16x32_bf16 v[80:83], v[154:157], v[190:193], v[80:83]
	s_barrier
	v_add_u32_e32 v206, 0x1c000, v139
	s_add_i32 m0, s18, 0x18000
	ds_read_b128 v[194:197], v206
	ds_read_b128 v[198:201], v206 offset:1024
	ds_read_b128 v[202:205], v206 offset:2048
	global_load_lds_dwordx4 v176, s[98:99]
	s_add_i32 m0, s18, 0x1a000
	ds_read_b128 v[206:209], v206 offset:3072
	global_load_lds_dwordx4 v128, s[98:99]
	s_barrier
	s_waitcnt lgkmcnt(3)
	v_mfma_f32_16x16x32_bf16 v[108:111], v[194:197], v[158:161], v[108:111]
	s_waitcnt lgkmcnt(1)
	v_mfma_f32_16x16x32_bf16 v[104:107], v[202:205], v[158:161], v[104:107]
	v_mfma_f32_16x16x32_bf16 v[92:95], v[194:197], v[166:169], v[92:95]
	v_mfma_f32_16x16x32_bf16 v[88:91], v[202:205], v[166:169], v[88:91]
	v_mfma_f32_16x16x32_bf16 v[76:79], v[194:197], v[178:181], v[76:79]
	v_mfma_f32_16x16x32_bf16 v[72:75], v[202:205], v[178:181], v[72:75]
	v_mfma_f32_16x16x32_bf16 v[68:71], v[194:197], v[186:189], v[68:71]
	v_mfma_f32_16x16x32_bf16 v[64:67], v[202:205], v[186:189], v[64:67]
	v_mfma_f32_16x16x32_bf16 v[108:111], v[198:201], v[162:165], v[108:111]
	s_waitcnt lgkmcnt(0)
	v_mfma_f32_16x16x32_bf16 v[104:107], v[206:209], v[162:165], v[104:107]
	v_mfma_f32_16x16x32_bf16 v[92:95], v[198:201], v[170:173], v[92:95]
	v_mfma_f32_16x16x32_bf16 v[88:91], v[206:209], v[170:173], v[88:91]
	v_mfma_f32_16x16x32_bf16 v[76:79], v[198:201], v[182:185], v[76:79]
	v_mfma_f32_16x16x32_bf16 v[72:75], v[206:209], v[182:185], v[72:75]
	v_mfma_f32_16x16x32_bf16 v[68:71], v[198:201], v[190:193], v[68:71]
	v_mfma_f32_16x16x32_bf16 v[64:67], v[206:209], v[190:193], v[64:67]
	s_mov_b32 m0, s27
	s_barrier
	ds_read_b128 v[158:161], v141 offset:49152
	ds_read_b128 v[162:165], v141 offset:50176
	ds_read_b128 v[166:169], v141 offset:51200
	ds_read_b128 v[170:173], v141 offset:52224
	ds_read_b128 v[178:181], v141 offset:53248
	ds_read_b128 v[182:185], v141 offset:54272
	ds_read_b128 v[186:189], v141 offset:55296
	global_load_lds_dwordx4 v132, s[100:101]
	s_mov_b32 m0, s28
	ds_read_b128 v[190:193], v141 offset:56320
	global_load_lds_dwordx4 v130, s[100:101]
	s_barrier
; #define PG8_STAGE(bufoff, gbase, voff) do { _Pragma("unroll") for (int _i = 0; _i < 2; ++_i) \
;         __builtin_amdgcn_global_load_lds((const unsigned*)((const char*)(gbase) + (voff)[_i]), (PG8_LAS unsigned*)(lds + (bufoff) + ldsw + _i * 8192), 16, 0, 0); } while (0)
; #define PG8_MMA(ai, bj, At, Bt) do { __builtin_amdgcn_s_setprio(1); _Pragma("unroll") for (int m = 0; m < 4; ++m) _Pragma("unroll") for (int n = 0; n < 2; ++n) _Pragma("unroll") for (int k = 0; k < 2; ++k) \
;         acc[ai][bj][m][n] = __builtin_amdgcn_mfma_f32_16x16x32_bf16(Bt[n][k], At[m][k], acc[ai][bj][m][n], 0, 0, 0); __builtin_amdgcn_s_setprio(0); } while (0)
; #define PG8_WAIT_V(n) asm volatile("s_waitcnt vmcnt(" #n ")" ::: "memory")
; #define PG8_WAIT_L(n) asm volatile("s_waitcnt lgkmcnt(" #n ")" ::: "memory")
; #define PG8_BAR __builtin_amdgcn_s_barrier()
; #define PG8_SCHED __builtin_amdgcn_sched_barrier(0)
; template <class Epi, class Sched>
; __device__ __forceinline__ void gemm_phase(PG8_LAS unsigned char* lds, const Gemm g, const Sched& S, const Epi& E) {
;     ...
;             PG8_BAR; PG8_WAIT_L(0); PG8_MMA(1, 0, At, B0); PG8_BAR; PG8_SCHED;
;             PG8_STAGE(PG8_SB(1, 1), b3 + hstep, voffB);
;             PG8_WAIT_V(6); PG8_BAR; PG8_MMA(1, 1, At, B1); PG8_BAR;
;         }
	s_waitcnt lgkmcnt(7)
	v_mfma_f32_16x16x32_bf16 v[60:63], v[142:145], v[158:161], v[60:63]
	v_mfma_f32_16x16x32_bf16 v[56:59], v[150:153], v[158:161], v[56:59]
	s_waitcnt lgkmcnt(5)
	v_mfma_f32_16x16x32_bf16 v[52:55], v[142:145], v[166:169], v[52:55]
	v_mfma_f32_16x16x32_bf16 v[48:51], v[150:153], v[166:169], v[48:51]
	s_waitcnt lgkmcnt(3)
	v_mfma_f32_16x16x32_bf16 v[36:39], v[142:145], v[178:181], v[36:39]
	v_mfma_f32_16x16x32_bf16 v[32:35], v[150:153], v[178:181], v[32:35]
	s_waitcnt lgkmcnt(1)
	v_mfma_f32_16x16x32_bf16 v[20:23], v[142:145], v[186:189], v[20:23]
	v_mfma_f32_16x16x32_bf16 v[16:19], v[150:153], v[186:189], v[16:19]
	v_mfma_f32_16x16x32_bf16 v[60:63], v[146:149], v[162:165], v[60:63]
	v_mfma_f32_16x16x32_bf16 v[56:59], v[154:157], v[162:165], v[56:59]
	v_mfma_f32_16x16x32_bf16 v[52:55], v[146:149], v[170:173], v[52:55]
	v_mfma_f32_16x16x32_bf16 v[48:51], v[154:157], v[170:173], v[48:51]
	v_mfma_f32_16x16x32_bf16 v[36:39], v[146:149], v[182:185], v[36:39]
	v_mfma_f32_16x16x32_bf16 v[32:35], v[154:157], v[182:185], v[32:35]
	s_waitcnt lgkmcnt(0)
	v_mfma_f32_16x16x32_bf16 v[20:23], v[146:149], v[190:193], v[20:23]
	v_mfma_f32_16x16x32_bf16 v[16:19], v[154:157], v[190:193], v[16:19]
	s_barrier
	s_add_u32 s8, s12, 0xb0080
	s_addc_u32 s9, s13, 0
	s_add_i32 m0, s18, 0x1c000
	s_nop 0
	global_load_lds_dwordx4 v176, s[8:9]
	s_add_i32 m0, s18, 0x1e000
	s_nop 0
	global_load_lds_dwordx4 v128, s[8:9]
	s_waitcnt vmcnt(6)
	s_barrier
	v_mfma_f32_16x16x32_bf16 v[44:47], v[194:197], v[158:161], v[44:47]
	v_mfma_f32_16x16x32_bf16 v[40:43], v[202:205], v[158:161], v[40:43]
	v_mfma_f32_16x16x32_bf16 v[28:31], v[194:197], v[166:169], v[28:31]
	v_mfma_f32_16x16x32_bf16 v[24:27], v[202:205], v[166:169], v[24:27]
	v_mfma_f32_16x16x32_bf16 v[12:15], v[194:197], v[178:181], v[12:15]
	v_mfma_f32_16x16x32_bf16 v[8:11], v[202:205], v[178:181], v[8:11]
	v_mfma_f32_16x16x32_bf16 v[4:7], v[194:197], v[186:189], v[4:7]
	v_mfma_f32_16x16x32_bf16 v[0:3], v[202:205], v[186:189], v[0:3]
	v_mfma_f32_16x16x32_bf16 v[44:47], v[198:201], v[162:165], v[44:47]
	v_mfma_f32_16x16x32_bf16 v[40:43], v[206:209], v[162:165], v[40:43]
	v_mfma_f32_16x16x32_bf16 v[28:31], v[198:201], v[170:173], v[28:31]
	v_mfma_f32_16x16x32_bf16 v[24:27], v[206:209], v[170:173], v[24:27]
	v_mfma_f32_16x16x32_bf16 v[12:15], v[198:201], v[182:185], v[12:15]
	v_mfma_f32_16x16x32_bf16 v[8:11], v[206:209], v[182:185], v[8:11]
	v_mfma_f32_16x16x32_bf16 v[4:7], v[198:201], v[190:193], v[4:7]
	v_mfma_f32_16x16x32_bf16 v[0:3], v[206:209], v[190:193], v[0:3]
	s_add_i32 s45, s45, 2
	s_add_u32 s43, s43, 0x100
	s_addc_u32 s44, s44, 0
	s_cmp_gt_u32 s45, 41
	s_mov_b64 s[8:9], s[10:11]
	s_barrier
	s_cbranch_scc0 .LBB0_96
; __device__ __forceinline__ unsigned cvtpk(float lo, float hi) { const f32x2 v = (f32x2){lo, hi}; const bf16v2 b = __builtin_convertvector(v, bf16v2); return __builtin_bit_cast(unsigned, b); }
;     __device__ __forceinline__ void operator()(const f32x4 (&acc)[2][2][4][2], const pg8::Unit& u, int wr, int wc, int fr, int fq) const {
;         const int row0 = u.pm * 256 + wr * 64 + fr, col0 = u.pn * 256 + wc * 32 + 8 * fq;
; #pragma unroll
;         for (int ai = 0; ai < 2; ++ai)
; #pragma unroll
;             for (int m = 0; m < 4; ++m) { bf16_t* rowp = O + (size_t)(row0 + ai * 128 + m * 16) * ldc + col0;
; #pragma unroll
;                 for (int bj = 0; bj < 2; ++bj) { const f32x4 v0 = acc[ai][bj][m][0], v1 = acc[ai][bj][m][1];
;                     u32x4 w; w.x = cvtpk(v0[0], v0[1]); w.y = cvtpk(v0[2], v0[3]); w.z = cvtpk(v1[0], v1[1]); w.w = cvtpk(v1[2], v1[3]);
;                     *(u32x4*)(rowp + bj * 128) = w; } }
;     }
	v_lshl_add_u32 v142, s29, 8, v138
	v_lshl_or_b32 v144, s34, 8, v140
	v_ashrrev_i32_e32 v143, 31, v142
	v_readlane_b32 s8, v253, 18
	v_cvt_pk_bf16_f32 v108, v108, v109
	v_cvt_pk_bf16_f32 v109, v110, v111
	v_cvt_pk_bf16_f32 v110, v104, v105
	v_or_b32_e32 v104, 16, v142
	v_cvt_pk_bf16_f32 v92, v92, v93
	v_cvt_pk_bf16_f32 v93, v94, v95
	v_cvt_pk_bf16_f32 v94, v88, v89
	v_or_b32_e32 v88, 32, v142
	v_cvt_pk_bf16_f32 v76, v76, v77
	v_cvt_pk_bf16_f32 v77, v78, v79
	v_cvt_pk_bf16_f32 v78, v72, v73
	v_or_b32_e32 v72, 48, v142
	v_ashrrev_i32_e32 v145, 31, v144
	v_lshlrev_b64 v[146:147], 11, v[142:143]
	v_readlane_b32 s9, v253, 19
	v_ashrrev_i32_e32 v105, 31, v104
	v_ashrrev_i32_e32 v89, 31, v88
	v_ashrrev_i32_e32 v73, 31, v72
	v_lshl_add_u64 v[146:147], s[8:9], 0, v[146:147]
	v_lshlrev_b64 v[144:145], 1, v[144:145]
	v_lshlrev_b64 v[104:105], 11, v[104:105]
	v_lshlrev_b64 v[88:89], 11, v[88:89]
	v_lshlrev_b64 v[72:73], 11, v[72:73]
	v_lshl_add_u64 v[146:147], v[146:147], 0, v[144:145]
	v_lshl_add_u64 v[104:105], s[8:9], 0, v[104:105]
	v_lshl_add_u64 v[88:89], s[8:9], 0, v[88:89]
	v_lshl_add_u64 v[72:73], s[8:9], 0, v[72:73]
	s_mov_b64 s[8:9], 0x40000
	v_cvt_pk_bf16_f32 v68, v68, v69
	v_cvt_pk_bf16_f32 v69, v70, v71
	v_cvt_pk_bf16_f32 v70, v64, v65
	v_lshl_add_u64 v[64:65], v[146:147], 0, s[8:9]
	v_cvt_pk_bf16_f32 v60, v60, v61
	v_cvt_pk_bf16_f32 v61, v62, v63
	v_cvt_pk_bf16_f32 v62, v56, v57
	v_add_co_u32_e32 v56, vcc, s2, v146
	v_cvt_pk_bf16_f32 v44, v44, v45
	v_cvt_pk_bf16_f32 v45, v46, v47
	v_cvt_pk_bf16_f32 v46, v40, v41
	v_cvt_pk_bf16_f32 v47, v42, v43
	s_mov_b64 s[8:9], 0x48000
	v_addc_co_u32_e32 v57, vcc, 0, v147, vcc
	global_store_dwordx4 v[64:65], v[44:47], off offset:256 sc1
	v_cvt_pk_bf16_f32 v28, v28, v29
	v_cvt_pk_bf16_f32 v29, v30, v31
	v_lshl_add_u64 v[44:45], v[146:147], 0, s[8:9]
	s_mov_b32 s8, 0x48000
	v_add_co_u32_e32 v46, vcc, s8, v146
	v_cvt_pk_bf16_f32 v30, v24, v25
	v_cvt_pk_bf16_f32 v31, v26, v27
	s_mov_b64 s[8:9], 0x50000
	v_addc_co_u32_e32 v47, vcc, 0, v147, vcc
	global_store_dwordx4 v[44:45], v[28:31], off offset:256 sc1
	v_cvt_pk_bf16_f32 v12, v12, v13
	v_cvt_pk_bf16_f32 v13, v14, v15
	v_lshl_add_u64 v[28:29], v[146:147], 0, s[8:9]
	s_mov_b32 s8, 0x50000
	v_add_co_u32_e32 v30, vcc, s8, v146
	v_cvt_pk_bf16_f32 v14, v8, v9
	v_cvt_pk_bf16_f32 v15, v10, v11
	s_mov_b64 s[8:9], 0x58000
	v_cvt_pk_bf16_f32 v111, v106, v107
	v_addc_co_u32_e32 v31, vcc, 0, v147, vcc
	global_store_dwordx4 v[28:29], v[12:15], off offset:256 sc1
	global_store_dwordx4 v[146:147], v[108:111], off offset:256 sc1
	v_cvt_pk_bf16_f32 v95, v90, v91
	v_lshl_add_u64 v[12:13], v[146:147], 0, s[8:9]
	s_mov_b32 s8, 0x58000
	v_lshl_add_u64 v[108:109], v[104:105], 0, v[144:145]
	v_add_co_u32_e32 v14, vcc, s8, v146
	global_store_dwordx4 v[108:109], v[92:95], off offset:256 sc1
	v_cvt_pk_bf16_f32 v79, v74, v75
	v_addc_co_u32_e32 v15, vcc, 0, v147, vcc
	v_lshl_add_u64 v[92:93], v[88:89], 0, v[144:145]
	v_cvt_pk_bf16_f32 v124, v124, v125
	v_cvt_pk_bf16_f32 v125, v126, v127
	v_cvt_pk_bf16_f32 v126, v120, v121
	v_cvt_pk_bf16_f32 v127, v122, v123
	v_cvt_pk_bf16_f32 v104, v116, v117
	v_cvt_pk_bf16_f32 v105, v118, v119
	v_cvt_pk_bf16_f32 v106, v112, v113
	v_cvt_pk_bf16_f32 v107, v114, v115
	v_cvt_pk_bf16_f32 v88, v100, v101
	v_cvt_pk_bf16_f32 v89, v102, v103
	v_cvt_pk_bf16_f32 v90, v96, v97
	v_cvt_pk_bf16_f32 v91, v98, v99
	global_store_dwordx4 v[92:93], v[76:79], off offset:256 sc1
	v_cvt_pk_bf16_f32 v74, v80, v81
	v_cvt_pk_bf16_f32 v75, v82, v83
	v_lshl_add_u64 v[76:77], v[72:73], 0, v[144:145]
	v_cvt_pk_bf16_f32 v72, v84, v85
	v_cvt_pk_bf16_f32 v73, v86, v87
	v_cvt_pk_bf16_f32 v71, v66, v67
	v_cvt_pk_bf16_f32 v63, v58, v59
	v_cvt_pk_bf16_f32 v40, v52, v53
	v_cvt_pk_bf16_f32 v41, v54, v55
	v_cvt_pk_bf16_f32 v42, v48, v49
	v_cvt_pk_bf16_f32 v43, v50, v51
	v_cvt_pk_bf16_f32 v24, v36, v37
	v_cvt_pk_bf16_f32 v25, v38, v39
	v_cvt_pk_bf16_f32 v26, v32, v33
	v_cvt_pk_bf16_f32 v27, v34, v35
	v_cvt_pk_bf16_f32 v8, v20, v21
	v_cvt_pk_bf16_f32 v9, v22, v23
	v_cvt_pk_bf16_f32 v10, v16, v17
	v_cvt_pk_bf16_f32 v11, v18, v19
	v_cvt_pk_bf16_f32 v4, v4, v5
	v_cvt_pk_bf16_f32 v5, v6, v7
	v_cvt_pk_bf16_f32 v6, v0, v1
	v_cvt_pk_bf16_f32 v7, v2, v3
	s_and_b64 vcc, exec, s[38:39]
	s_mov_b32 s34, s40
	s_mov_b32 s29, s41
	s_mov_b64 s[10:11], s[4:5]
	s_mov_b64 s[8:9], s[0:1]
	global_store_dwordx4 v[146:147], v[124:127], off sc1
	global_store_dwordx4 v[108:109], v[104:107], off sc1
	global_store_dwordx4 v[92:93], v[88:91], off sc1
	global_store_dwordx4 v[76:77], v[72:75], off sc1
	global_store_dwordx4 v[76:77], v[68:71], off offset:256 sc1
	global_store_dwordx4 v[56:57], v[60:63], off sc1
	global_store_dwordx4 v[46:47], v[40:43], off sc1
	global_store_dwordx4 v[30:31], v[24:27], off sc1
	global_store_dwordx4 v[14:15], v[8:11], off sc1
	global_store_dwordx4 v[12:13], v[4:7], off offset:256 sc1
	s_cbranch_vccz .LBB0_89
	s_waitcnt vmcnt(0)
	s_cmpk_gt_u32 s17, 0xff
	v_readlane_b32 s2, v254, 59
	s_cbranch_scc1 .LBB0_100
	s_barrier

; #define PG8_STAGE(bufoff, gbase, voff) do { _Pragma("unroll") for (int _i = 0; _i < 2; ++_i) \
;         __builtin_amdgcn_global_load_lds((const unsigned*)((const char*)(gbase) + (voff)[_i]), (PG8_LAS unsigned*)(lds + (bufoff) + ldsw + _i * 8192), 16, 0, 0); } while (0)
; #define PG8_LDA(dst, b, h) do { _Pragma("unroll") for (int m = 0; m < 4; ++m) _Pragma("unroll") for (int k = 0; k < 2; ++k) dst[m][k] = *(const PG8_LAS bf16x8*)(lds + PG8_SA(b, h) + aoff + m * 2048 + k * 1024); } while (0)
; #define PG8_LDB(dst, b, h) do { _Pragma("unroll") for (int n = 0; n < 2; ++n) _Pragma("unroll") for (int k = 0; k < 2; ++k) dst[n][k] = *(const PG8_LAS bf16x8*)(lds + PG8_SB(b, h) + boff + n * 2048 + k * 1024); } while (0)
; #define PG8_MMA(ai, bj, At, Bt) do { __builtin_amdgcn_s_setprio(1); _Pragma("unroll") for (int m = 0; m < 4; ++m) _Pragma("unroll") for (int n = 0; n < 2; ++n) _Pragma("unroll") for (int k = 0; k < 2; ++k) \
;         acc[ai][bj][m][n] = __builtin_amdgcn_mfma_f32_16x16x32_bf16(Bt[n][k], At[m][k], acc[ai][bj][m][n], 0, 0, 0); __builtin_amdgcn_s_setprio(0); } while (0)
; #define PG8_WAIT_V(n) asm volatile("s_waitcnt vmcnt(" #n ")" ::: "memory")
; #define PG8_WAIT_L(n) asm volatile("s_waitcnt lgkmcnt(" #n ")" ::: "memory")
; #define PG8_BAR __builtin_amdgcn_s_barrier()
; #define PG8_SCHED __builtin_amdgcn_sched_barrier(0)
; template <class Epi, class Sched>
; __device__ __forceinline__ void gemm_phase(PG8_LAS unsigned char* lds, const Gemm g, const Sched& S, const Epi& E) {
;     ...
;             PG8_LDB(B0, 0, 0); PG8_SCHED; PG8_LDA(At, 0, 0); PG8_STAGE(PG8_SA(1, 1), a1 + hstep, voffA);
;             PG8_WAIT_L(8); PG8_BAR; PG8_WAIT_L(0); PG8_MMA(0, 0, At, B0); PG8_BAR; PG8_SCHED;
;             PG8_LDB(B1, 0, 1); PG8_STAGE(PG8_SB(0, 0), b2, voffB);
;             PG8_BAR; PG8_WAIT_L(0); PG8_MMA(0, 1, At, B1); PG8_BAR;
;             PG8_LDA(At, 0, 1); PG8_STAGE(PG8_SA(0, 0), a2, voffA);
;             PG8_BAR; PG8_WAIT_L(0); PG8_MMA(1, 0, At, B0); PG8_BAR; PG8_SCHED;
;             PG8_STAGE(PG8_SB(0, 1), b2 + hstep, voffB);
;             PG8_WAIT_V(6); PG8_BAR; PG8_MMA(1, 1, At, B1); PG8_BAR;
.LBB0_114:
	s_add_u32 s14, s12, 0xfffc0080
	s_addc_u32 s15, s13, -1
	v_add_u32_e32 v154, 0x10000, v143
	ds_read_b128 v[138:141], v154
	ds_read_b128 v[146:149], v154 offset:1024
	ds_read_b128 v[150:153], v154 offset:2048
	ds_read_b128 v[154:157], v154 offset:3072
	s_cmp_eq_u32 s45, 12
	s_cselect_b32 s17, s5, s15
	s_cselect_b32 s16, s40, s14
	s_cselect_b32 s15, s1, s44
	s_cselect_b32 s14, s41, s43
	s_add_i32 m0, s11, 0xc000
	ds_read_b128 v[158:161], v145
	ds_read_b128 v[162:165], v145 offset:1024
	ds_read_b128 v[166:169], v145 offset:2048
	ds_read_b128 v[170:173], v145 offset:3072
	ds_read_b128 v[178:181], v145 offset:4096
	ds_read_b128 v[182:185], v145 offset:5120
	ds_read_b128 v[186:189], v145 offset:6144
	global_load_lds_dwordx4 v134, s[12:13]
	s_add_i32 m0, s11, 0xe000
	ds_read_b128 v[190:193], v145 offset:7168
	global_load_lds_dwordx4 v136, s[12:13]
	s_waitcnt lgkmcnt(8)
	s_barrier
	s_waitcnt lgkmcnt(7)
	v_mfma_f32_16x16x32_bf16 v[124:127], v[138:141], v[158:161], v[124:127]
	v_mfma_f32_16x16x32_bf16 v[116:119], v[150:153], v[158:161], v[116:119]
	s_waitcnt lgkmcnt(5)
	v_mfma_f32_16x16x32_bf16 v[108:111], v[138:141], v[166:169], v[108:111]
	v_mfma_f32_16x16x32_bf16 v[100:103], v[150:153], v[166:169], v[100:103]
	s_waitcnt lgkmcnt(3)
	v_mfma_f32_16x16x32_bf16 v[92:95], v[138:141], v[178:181], v[92:95]
	v_mfma_f32_16x16x32_bf16 v[84:87], v[150:153], v[178:181], v[84:87]
	s_waitcnt lgkmcnt(1)
	v_mfma_f32_16x16x32_bf16 v[76:79], v[138:141], v[186:189], v[76:79]
	v_mfma_f32_16x16x32_bf16 v[68:71], v[150:153], v[186:189], v[68:71]
	v_mfma_f32_16x16x32_bf16 v[124:127], v[146:149], v[162:165], v[124:127]
	v_mfma_f32_16x16x32_bf16 v[116:119], v[154:157], v[162:165], v[116:119]
	v_mfma_f32_16x16x32_bf16 v[108:111], v[146:149], v[170:173], v[108:111]
	v_mfma_f32_16x16x32_bf16 v[100:103], v[154:157], v[170:173], v[100:103]
	v_mfma_f32_16x16x32_bf16 v[92:95], v[146:149], v[182:185], v[92:95]
	v_mfma_f32_16x16x32_bf16 v[84:87], v[154:157], v[182:185], v[84:87]
	s_waitcnt lgkmcnt(0)
	v_mfma_f32_16x16x32_bf16 v[76:79], v[146:149], v[190:193], v[76:79]
	v_mfma_f32_16x16x32_bf16 v[68:71], v[154:157], v[190:193], v[68:71]
	s_barrier
	s_add_i32 s48, 0, 0x14000
	v_add_u32_e32 v174, 0x14000, v143
	ds_read_b128 v[194:197], v174
	ds_read_b128 v[198:201], v174 offset:1024
	s_add_u32 s98, s14, 0x80
	s_addc_u32 s99, s15, 0
	s_add_i32 m0, s20, 0x10000
	ds_read_b128 v[202:205], v174 offset:2048
	global_load_lds_dwordx4 v176, s[14:15]
	s_add_i32 m0, s20, 0x12000
	ds_read_b128 v[206:209], v174 offset:3072
	global_load_lds_dwordx4 v128, s[14:15]
	s_barrier
	s_waitcnt lgkmcnt(3)
	v_mfma_f32_16x16x32_bf16 v[120:123], v[194:197], v[158:161], v[120:123]
	s_waitcnt lgkmcnt(1)
	v_mfma_f32_16x16x32_bf16 v[112:115], v[202:205], v[158:161], v[112:115]
	v_mfma_f32_16x16x32_bf16 v[104:107], v[194:197], v[166:169], v[104:107]
	v_mfma_f32_16x16x32_bf16 v[96:99], v[202:205], v[166:169], v[96:99]
	v_mfma_f32_16x16x32_bf16 v[88:91], v[194:197], v[178:181], v[88:91]
	v_mfma_f32_16x16x32_bf16 v[80:83], v[202:205], v[178:181], v[80:83]
	v_mfma_f32_16x16x32_bf16 v[72:75], v[194:197], v[186:189], v[72:75]
	v_mfma_f32_16x16x32_bf16 v[64:67], v[202:205], v[186:189], v[64:67]
	v_mfma_f32_16x16x32_bf16 v[120:123], v[198:201], v[162:165], v[120:123]
	s_waitcnt lgkmcnt(0)
	v_mfma_f32_16x16x32_bf16 v[112:115], v[206:209], v[162:165], v[112:115]
	v_mfma_f32_16x16x32_bf16 v[104:107], v[198:201], v[170:173], v[104:107]
	v_mfma_f32_16x16x32_bf16 v[96:99], v[206:209], v[170:173], v[96:99]
	v_mfma_f32_16x16x32_bf16 v[88:91], v[198:201], v[182:185], v[88:91]
	v_mfma_f32_16x16x32_bf16 v[80:83], v[206:209], v[182:185], v[80:83]
	v_mfma_f32_16x16x32_bf16 v[72:75], v[198:201], v[190:193], v[72:75]
	v_mfma_f32_16x16x32_bf16 v[64:67], v[206:209], v[190:193], v[64:67]
	s_mov_b32 m0, s11
	s_add_u32 s100, s16, 0x80
	s_addc_u32 s101, s17, 0
	s_barrier
	ds_read_b128 v[158:161], v145 offset:16384
	ds_read_b128 v[162:165], v145 offset:17408
	ds_read_b128 v[166:169], v145 offset:18432
	ds_read_b128 v[170:173], v145 offset:19456
	ds_read_b128 v[178:181], v145 offset:20480
	ds_read_b128 v[182:185], v145 offset:21504
	ds_read_b128 v[186:189], v145 offset:22528
	global_load_lds_dwordx4 v132, s[16:17]
	s_mov_b32 m0, s22
	ds_read_b128 v[190:193], v145 offset:23552
	global_load_lds_dwordx4 v130, s[16:17]
	s_barrier
	s_waitcnt lgkmcnt(7)
	v_mfma_f32_16x16x32_bf16 v[60:63], v[138:141], v[158:161], v[60:63]
	v_mfma_f32_16x16x32_bf16 v[52:55], v[150:153], v[158:161], v[52:55]
	s_waitcnt lgkmcnt(5)
	v_mfma_f32_16x16x32_bf16 v[44:47], v[138:141], v[166:169], v[44:47]
	v_mfma_f32_16x16x32_bf16 v[36:39], v[150:153], v[166:169], v[36:39]
	s_waitcnt lgkmcnt(3)
	v_mfma_f32_16x16x32_bf16 v[28:31], v[138:141], v[178:181], v[28:31]
	v_mfma_f32_16x16x32_bf16 v[20:23], v[150:153], v[178:181], v[20:23]
	s_waitcnt lgkmcnt(1)
	v_mfma_f32_16x16x32_bf16 v[12:15], v[138:141], v[186:189], v[12:15]
	v_mfma_f32_16x16x32_bf16 v[4:7], v[150:153], v[186:189], v[4:7]
	v_mfma_f32_16x16x32_bf16 v[60:63], v[146:149], v[162:165], v[60:63]
	v_mfma_f32_16x16x32_bf16 v[52:55], v[154:157], v[162:165], v[52:55]
	v_mfma_f32_16x16x32_bf16 v[44:47], v[146:149], v[170:173], v[44:47]
	v_mfma_f32_16x16x32_bf16 v[36:39], v[154:157], v[170:173], v[36:39]
	v_mfma_f32_16x16x32_bf16 v[28:31], v[146:149], v[182:185], v[28:31]
	v_mfma_f32_16x16x32_bf16 v[20:23], v[154:157], v[182:185], v[20:23]
	s_waitcnt lgkmcnt(0)
	v_mfma_f32_16x16x32_bf16 v[12:15], v[146:149], v[190:193], v[12:15]
	v_mfma_f32_16x16x32_bf16 v[4:7], v[154:157], v[190:193], v[4:7]
	s_barrier
; #define PG8_STAGE(bufoff, gbase, voff) do { _Pragma("unroll") for (int _i = 0; _i < 2; ++_i) \
;         __builtin_amdgcn_global_load_lds((const unsigned*)((const char*)(gbase) + (voff)[_i]), (PG8_LAS unsigned*)(lds + (bufoff) + ldsw + _i * 8192), 16, 0, 0); } while (0)
; #define PG8_LDA(dst, b, h) do { _Pragma("unroll") for (int m = 0; m < 4; ++m) _Pragma("unroll") for (int k = 0; k < 2; ++k) dst[m][k] = *(const PG8_LAS bf16x8*)(lds + PG8_SA(b, h) + aoff + m * 2048 + k * 1024); } while (0)
; #define PG8_LDB(dst, b, h) do { _Pragma("unroll") for (int n = 0; n < 2; ++n) _Pragma("unroll") for (int k = 0; k < 2; ++k) dst[n][k] = *(const PG8_LAS bf16x8*)(lds + PG8_SB(b, h) + boff + n * 2048 + k * 1024); } while (0)
; #define PG8_MMA(ai, bj, At, Bt) do { __builtin_amdgcn_s_setprio(1); _Pragma("unroll") for (int m = 0; m < 4; ++m) _Pragma("unroll") for (int n = 0; n < 2; ++n) _Pragma("unroll") for (int k = 0; k < 2; ++k) \
;         acc[ai][bj][m][n] = __builtin_amdgcn_mfma_f32_16x16x32_bf16(Bt[n][k], At[m][k], acc[ai][bj][m][n], 0, 0, 0); __builtin_amdgcn_s_setprio(0); } while (0)
; #define PG8_WAIT_V(n) asm volatile("s_waitcnt vmcnt(" #n ")" ::: "memory")
; #define PG8_WAIT_L(n) asm volatile("s_waitcnt lgkmcnt(" #n ")" ::: "memory")
; #define PG8_BAR __builtin_amdgcn_s_barrier()
; #define PG8_SCHED __builtin_amdgcn_sched_barrier(0)
; template <class Epi, class Sched>
; __device__ __forceinline__ void gemm_phase(PG8_LAS unsigned char* lds, const Gemm g, const Sched& S, const Epi& E) {
;     ...
;             PG8_STAGE(PG8_SB(0, 1), b2 + hstep, voffB);
;             PG8_WAIT_V(6); PG8_BAR; PG8_MMA(1, 1, At, B1); PG8_BAR;
;             PG8_LDB(B0, 1, 0); PG8_SCHED; PG8_LDA(At, 1, 0); PG8_STAGE(PG8_SA(0, 1), a2 + hstep, voffA);
;             PG8_WAIT_L(8); PG8_BAR; PG8_WAIT_L(0); PG8_MMA(0, 0, At, B0); PG8_BAR; PG8_SCHED;
;             PG8_LDB(B1, 1, 1); PG8_STAGE(PG8_SB(1, 0), b3, voffB);
;             PG8_BAR; PG8_WAIT_L(0); PG8_MMA(0, 1, At, B1); PG8_BAR;
;             PG8_LDA(At, 1, 1); PG8_STAGE(PG8_SA(1, 0), a3, voffA);
;             PG8_BAR; PG8_WAIT_L(0); PG8_MMA(1, 0, At, B0); PG8_BAR; PG8_SCHED;
	s_add_u32 s46, s14, 0x40000
	s_addc_u32 s47, s15, 0
	s_add_i32 m0, s20, 0x14000
	s_nop 0
	global_load_lds_dwordx4 v176, s[46:47]
	s_add_i32 m0, s20, 0x16000
	s_nop 0
	global_load_lds_dwordx4 v128, s[46:47]
	s_waitcnt vmcnt(6)
	s_barrier
	v_mfma_f32_16x16x32_bf16 v[56:59], v[194:197], v[158:161], v[56:59]
	v_mfma_f32_16x16x32_bf16 v[48:51], v[202:205], v[158:161], v[48:51]
	v_mfma_f32_16x16x32_bf16 v[40:43], v[194:197], v[166:169], v[40:43]
	v_mfma_f32_16x16x32_bf16 v[32:35], v[202:205], v[166:169], v[32:35]
	v_mfma_f32_16x16x32_bf16 v[24:27], v[194:197], v[178:181], v[24:27]
	v_mfma_f32_16x16x32_bf16 v[16:19], v[202:205], v[178:181], v[16:19]
	v_mfma_f32_16x16x32_bf16 v[8:11], v[194:197], v[186:189], v[8:11]
	v_mfma_f32_16x16x32_bf16 v[0:3], v[202:205], v[186:189], v[0:3]
	v_mfma_f32_16x16x32_bf16 v[56:59], v[198:201], v[162:165], v[56:59]
	v_mfma_f32_16x16x32_bf16 v[48:51], v[206:209], v[162:165], v[48:51]
	v_mfma_f32_16x16x32_bf16 v[40:43], v[198:201], v[170:173], v[40:43]
	v_mfma_f32_16x16x32_bf16 v[32:35], v[206:209], v[170:173], v[32:35]
	v_mfma_f32_16x16x32_bf16 v[24:27], v[198:201], v[182:185], v[24:27]
	v_mfma_f32_16x16x32_bf16 v[16:19], v[206:209], v[182:185], v[16:19]
	v_mfma_f32_16x16x32_bf16 v[8:11], v[198:201], v[190:193], v[8:11]
	v_mfma_f32_16x16x32_bf16 v[0:3], v[206:209], v[190:193], v[0:3]
	v_add_u32_e32 v154, 0x18000, v143
	s_barrier
	ds_read_b128 v[138:141], v154
	ds_read_b128 v[146:149], v154 offset:1024
	ds_read_b128 v[150:153], v154 offset:2048
	ds_read_b128 v[154:157], v154 offset:3072
	s_add_u32 s16, s16, 0x40000
	s_addc_u32 s17, s17, 0
	s_mov_b32 m0, s23
	ds_read_b128 v[158:161], v145 offset:32768
	ds_read_b128 v[162:165], v145 offset:33792
	ds_read_b128 v[166:169], v145 offset:34816
	ds_read_b128 v[170:173], v145 offset:35840
	ds_read_b128 v[178:181], v145 offset:36864
	ds_read_b128 v[182:185], v145 offset:37888
	ds_read_b128 v[186:189], v145 offset:38912
	global_load_lds_dwordx4 v132, s[16:17]
	s_mov_b32 m0, s26
	ds_read_b128 v[190:193], v145 offset:39936
	global_load_lds_dwordx4 v130, s[16:17]
	s_waitcnt lgkmcnt(8)
	s_barrier
	s_waitcnt lgkmcnt(7)
	v_mfma_f32_16x16x32_bf16 v[124:127], v[138:141], v[158:161], v[124:127]
	v_mfma_f32_16x16x32_bf16 v[116:119], v[150:153], v[158:161], v[116:119]
	s_waitcnt lgkmcnt(5)
	v_mfma_f32_16x16x32_bf16 v[108:111], v[138:141], v[166:169], v[108:111]
	v_mfma_f32_16x16x32_bf16 v[100:103], v[150:153], v[166:169], v[100:103]
	s_waitcnt lgkmcnt(3)
	v_mfma_f32_16x16x32_bf16 v[92:95], v[138:141], v[178:181], v[92:95]
	v_mfma_f32_16x16x32_bf16 v[84:87], v[150:153], v[178:181], v[84:87]
	s_waitcnt lgkmcnt(1)
	v_mfma_f32_16x16x32_bf16 v[76:79], v[138:141], v[186:189], v[76:79]
	v_mfma_f32_16x16x32_bf16 v[68:71], v[150:153], v[186:189], v[68:71]
	v_mfma_f32_16x16x32_bf16 v[124:127], v[146:149], v[162:165], v[124:127]
	v_mfma_f32_16x16x32_bf16 v[116:119], v[154:157], v[162:165], v[116:119]
	v_mfma_f32_16x16x32_bf16 v[108:111], v[146:149], v[170:173], v[108:111]
	v_mfma_f32_16x16x32_bf16 v[100:103], v[154:157], v[170:173], v[100:103]
	v_mfma_f32_16x16x32_bf16 v[92:95], v[146:149], v[182:185], v[92:95]
	v_mfma_f32_16x16x32_bf16 v[84:87], v[154:157], v[182:185], v[84:87]
	s_waitcnt lgkmcnt(0)
	v_mfma_f32_16x16x32_bf16 v[76:79], v[146:149], v[190:193], v[76:79]
	v_mfma_f32_16x16x32_bf16 v[68:71], v[154:157], v[190:193], v[68:71]
	s_barrier
	v_add_u32_e32 v206, 0x1c000, v143
	s_add_i32 m0, s20, 0x18000
	ds_read_b128 v[194:197], v206
	ds_read_b128 v[198:201], v206 offset:1024
	ds_read_b128 v[202:205], v206 offset:2048
	global_load_lds_dwordx4 v176, s[98:99]
	s_add_i32 m0, s20, 0x1a000
	ds_read_b128 v[206:209], v206 offset:3072
	global_load_lds_dwordx4 v128, s[98:99]
	s_barrier
	s_waitcnt lgkmcnt(3)
	v_mfma_f32_16x16x32_bf16 v[120:123], v[194:197], v[158:161], v[120:123]
	s_waitcnt lgkmcnt(1)
	v_mfma_f32_16x16x32_bf16 v[112:115], v[202:205], v[158:161], v[112:115]
	v_mfma_f32_16x16x32_bf16 v[104:107], v[194:197], v[166:169], v[104:107]
	v_mfma_f32_16x16x32_bf16 v[96:99], v[202:205], v[166:169], v[96:99]
	v_mfma_f32_16x16x32_bf16 v[88:91], v[194:197], v[178:181], v[88:91]
	v_mfma_f32_16x16x32_bf16 v[80:83], v[202:205], v[178:181], v[80:83]
	v_mfma_f32_16x16x32_bf16 v[72:75], v[194:197], v[186:189], v[72:75]
	v_mfma_f32_16x16x32_bf16 v[64:67], v[202:205], v[186:189], v[64:67]
	v_mfma_f32_16x16x32_bf16 v[120:123], v[198:201], v[162:165], v[120:123]
	s_waitcnt lgkmcnt(0)
	v_mfma_f32_16x16x32_bf16 v[112:115], v[206:209], v[162:165], v[112:115]
	v_mfma_f32_16x16x32_bf16 v[104:107], v[198:201], v[170:173], v[104:107]
	v_mfma_f32_16x16x32_bf16 v[96:99], v[206:209], v[170:173], v[96:99]
	v_mfma_f32_16x16x32_bf16 v[88:91], v[198:201], v[182:185], v[88:91]
	v_mfma_f32_16x16x32_bf16 v[80:83], v[206:209], v[182:185], v[80:83]
	v_mfma_f32_16x16x32_bf16 v[72:75], v[198:201], v[190:193], v[72:75]
	v_mfma_f32_16x16x32_bf16 v[64:67], v[206:209], v[190:193], v[64:67]
	s_mov_b32 m0, s28
	s_barrier
	ds_read_b128 v[158:161], v145 offset:49152
	ds_read_b128 v[162:165], v145 offset:50176
	ds_read_b128 v[166:169], v145 offset:51200
	ds_read_b128 v[170:173], v145 offset:52224
	ds_read_b128 v[178:181], v145 offset:53248
	ds_read_b128 v[182:185], v145 offset:54272
	ds_read_b128 v[186:189], v145 offset:55296
	global_load_lds_dwordx4 v132, s[100:101]
	s_mov_b32 m0, s29
	ds_read_b128 v[190:193], v145 offset:56320
	global_load_lds_dwordx4 v130, s[100:101]
	s_barrier
; __device__ __forceinline__ unsigned cvtpk(float lo, float hi) { const f32x2 v = (f32x2){lo, hi}; const bf16v2 b = __builtin_convertvector(v, bf16v2); return __builtin_bit_cast(unsigned, b); }
; __device__ __forceinline__ float siluf_(float x) { return x * sigmoidf_(x); }
; #define PG8_STAGE(bufoff, gbase, voff) do { _Pragma("unroll") for (int _i = 0; _i < 2; ++_i) \
;         __builtin_amdgcn_global_load_lds((const unsigned*)((const char*)(gbase) + (voff)[_i]), (PG8_LAS unsigned*)(lds + (bufoff) + ldsw + _i * 8192), 16, 0, 0); } while (0)
; #define PG8_MMA(ai, bj, At, Bt) do { __builtin_amdgcn_s_setprio(1); _Pragma("unroll") for (int m = 0; m < 4; ++m) _Pragma("unroll") for (int n = 0; n < 2; ++n) _Pragma("unroll") for (int k = 0; k < 2; ++k) \
;         acc[ai][bj][m][n] = __builtin_amdgcn_mfma_f32_16x16x32_bf16(Bt[n][k], At[m][k], acc[ai][bj][m][n], 0, 0, 0); __builtin_amdgcn_s_setprio(0); } while (0)
; #define PG8_WAIT_V(n) asm volatile("s_waitcnt vmcnt(" #n ")" ::: "memory")
; #define PG8_WAIT_L(n) asm volatile("s_waitcnt lgkmcnt(" #n ")" ::: "memory")
; #define PG8_BAR __builtin_amdgcn_s_barrier()
; template <class Epi, class Sched>
; __device__ __forceinline__ void gemm_phase(PG8_LAS unsigned char* lds, const Gemm g, const Sched& S, const Epi& E) {
;     ...
;             PG8_BAR; PG8_WAIT_L(0); PG8_MMA(1, 0, At, B0); PG8_BAR; PG8_SCHED;
;             PG8_STAGE(PG8_SB(1, 1), b3 + hstep, voffB);
;             PG8_WAIT_V(6); PG8_BAR; PG8_MMA(1, 1, At, B1); PG8_BAR;
;     __device__ __forceinline__ void operator()(const f32x4 (&acc)[2][2][4][2], const pg8::Unit& u, int wr, int wc, int fr, int fq) const {
;         const int row0 = u.pm * 256 + wr * 64 + fr, col0 = u.pn * 128 + wc * 32 + 8 * fq;
; #pragma unroll
;         for (int ai = 0; ai < 2; ++ai)
; #pragma unroll
;             for (int m = 0; m < 4; ++m) { bf16_t* rowp = O + (size_t)(row0 + ai * 128 + m * 16) * ldc + col0;
;                 const f32x4 g0 = acc[ai][0][m][0], g1 = acc[ai][0][m][1], u0 = acc[ai][1][m][0], u1 = acc[ai][1][m][1];
;                 u32x4 w; w.x = cvtpk(siluf_(g0[0]) * u0[0], siluf_(g0[1]) * u0[1]); w.y = cvtpk(siluf_(g0[2]) * u0[2], siluf_(g0[3]) * u0[3]);
;                 w.z = cvtpk(siluf_(g1[0]) * u1[0], siluf_(g1[1]) * u1[1]); w.w = cvtpk(siluf_(g1[2]) * u1[2], siluf_(g1[3]) * u1[3]);
;                 *(u32x4*)rowp = w; }
	s_waitcnt lgkmcnt(7)
	v_mfma_f32_16x16x32_bf16 v[60:63], v[138:141], v[158:161], v[60:63]
	v_mfma_f32_16x16x32_bf16 v[52:55], v[150:153], v[158:161], v[52:55]
	s_waitcnt lgkmcnt(5)
	v_mfma_f32_16x16x32_bf16 v[44:47], v[138:141], v[166:169], v[44:47]
	v_mfma_f32_16x16x32_bf16 v[36:39], v[150:153], v[166:169], v[36:39]
	s_waitcnt lgkmcnt(3)
	v_mfma_f32_16x16x32_bf16 v[28:31], v[138:141], v[178:181], v[28:31]
	v_mfma_f32_16x16x32_bf16 v[20:23], v[150:153], v[178:181], v[20:23]
	s_waitcnt lgkmcnt(1)
	v_mfma_f32_16x16x32_bf16 v[12:15], v[138:141], v[186:189], v[12:15]
	v_mfma_f32_16x16x32_bf16 v[4:7], v[150:153], v[186:189], v[4:7]
	v_mfma_f32_16x16x32_bf16 v[60:63], v[146:149], v[162:165], v[60:63]
	v_mfma_f32_16x16x32_bf16 v[52:55], v[154:157], v[162:165], v[52:55]
	v_mfma_f32_16x16x32_bf16 v[44:47], v[146:149], v[170:173], v[44:47]
	v_mfma_f32_16x16x32_bf16 v[36:39], v[154:157], v[170:173], v[36:39]
	v_mfma_f32_16x16x32_bf16 v[28:31], v[146:149], v[182:185], v[28:31]
	v_mfma_f32_16x16x32_bf16 v[20:23], v[154:157], v[182:185], v[20:23]
	s_waitcnt lgkmcnt(0)
	v_mfma_f32_16x16x32_bf16 v[12:15], v[146:149], v[190:193], v[12:15]
	v_mfma_f32_16x16x32_bf16 v[4:7], v[154:157], v[190:193], v[4:7]
	s_barrier
	s_add_u32 s14, s14, 0x40080
	s_addc_u32 s15, s15, 0
	s_add_i32 m0, s20, 0x1c000
	s_nop 0
	global_load_lds_dwordx4 v176, s[14:15]
	s_add_i32 m0, s20, 0x1e000
	s_nop 0
	global_load_lds_dwordx4 v128, s[14:15]
	s_waitcnt vmcnt(6)
	s_barrier
	v_mfma_f32_16x16x32_bf16 v[56:59], v[194:197], v[158:161], v[56:59]
	v_mfma_f32_16x16x32_bf16 v[48:51], v[202:205], v[158:161], v[48:51]
	v_mfma_f32_16x16x32_bf16 v[40:43], v[194:197], v[166:169], v[40:43]
	v_mfma_f32_16x16x32_bf16 v[32:35], v[202:205], v[166:169], v[32:35]
	v_mfma_f32_16x16x32_bf16 v[24:27], v[194:197], v[178:181], v[24:27]
	v_mfma_f32_16x16x32_bf16 v[16:19], v[202:205], v[178:181], v[16:19]
	v_mfma_f32_16x16x32_bf16 v[8:11], v[194:197], v[186:189], v[8:11]
	v_mfma_f32_16x16x32_bf16 v[0:3], v[202:205], v[186:189], v[0:3]
	v_mfma_f32_16x16x32_bf16 v[56:59], v[198:201], v[162:165], v[56:59]
	v_mfma_f32_16x16x32_bf16 v[48:51], v[206:209], v[162:165], v[48:51]
	v_mfma_f32_16x16x32_bf16 v[40:43], v[198:201], v[170:173], v[40:43]
	v_mfma_f32_16x16x32_bf16 v[32:35], v[206:209], v[170:173], v[32:35]
	v_mfma_f32_16x16x32_bf16 v[24:27], v[198:201], v[182:185], v[24:27]
	v_mfma_f32_16x16x32_bf16 v[16:19], v[206:209], v[182:185], v[16:19]
	v_mfma_f32_16x16x32_bf16 v[8:11], v[198:201], v[190:193], v[8:11]
	v_mfma_f32_16x16x32_bf16 v[0:3], v[206:209], v[190:193], v[0:3]
	s_add_i32 s45, s45, 2
	s_add_u32 s12, s12, 0x100
	s_addc_u32 s13, s13, 0
	s_add_u32 s43, s43, 0x100
	s_addc_u32 s44, s44, 0
	s_cmp_gt_u32 s45, 13
	s_barrier
	s_cbranch_scc0 .LBB0_114
	v_mul_f32_e32 v147, 0xbfb8aa3b, v124
	v_exp_f32_e32 v147, v147
	v_readlane_b32 s12, v253, 16
	v_lshl_add_u32 v146, s10, 8, v142
	v_lshl_or_b32 v140, s34, 7, v144
	v_add_f32_e32 v147, 1.0, v147
	v_rcp_f32_e32 v150, v147
	v_mul_f32_e32 v147, 0xbfb8aa3b, v125
	v_exp_f32_e32 v147, v147
	v_readlane_b32 s13, v253, 17
	v_ashrrev_i32_e32 v141, 31, v140
	v_lshlrev_b64 v[140:141], 1, v[140:141]
	v_add_f32_e32 v147, 1.0, v147
	v_rcp_f32_e32 v151, v147
	v_mov_b64_e32 v[138:139], s[12:13]
	v_mad_i64_i32 v[148:149], s[12:13], v146, s81, v[138:139]
	v_pk_mul_f32 v[124:125], v[124:125], v[150:151]
	v_lshl_add_u64 v[148:149], v[148:149], 0, v[140:141]
	v_pk_mul_f32 v[120:121], v[124:125], v[120:121]
	s_and_b64 vcc, exec, s[38:39]
	v_cvt_pk_bf16_f32 v120, v120, v121
	v_mul_f32_e32 v121, 0xbfb8aa3b, v126
	v_exp_f32_e32 v121, v121
	s_mov_b32 s34, s0
	s_mov_b32 s10, s4
	s_mov_b64 s[14:15], s[8:9]
	v_add_f32_e32 v121, 1.0, v121
	v_rcp_f32_e32 v124, v121
	v_mul_f32_e32 v121, 0xbfb8aa3b, v127
	v_exp_f32_e32 v121, v121
	s_nop 0
	v_add_f32_e32 v121, 1.0, v121
	v_rcp_f32_e32 v125, v121
	s_nop 0
	v_pk_mul_f32 v[124:125], v[126:127], v[124:125]
	s_nop 0
	v_pk_mul_f32 v[122:123], v[124:125], v[122:123]
	s_nop 0
	v_cvt_pk_bf16_f32 v121, v122, v123
	v_mul_f32_e32 v122, 0xbfb8aa3b, v116
	v_mul_f32_e32 v123, 0xbfb8aa3b, v117
	v_exp_f32_e32 v122, v122
	v_exp_f32_e32 v123, v123
	v_add_f32_e32 v122, 1.0, v122
	v_add_f32_e32 v123, 1.0, v123
	v_rcp_f32_e32 v122, v122
	v_rcp_f32_e32 v123, v123
	s_nop 0
	v_pk_mul_f32 v[116:117], v[116:117], v[122:123]
	s_nop 0
	v_pk_mul_f32 v[112:113], v[116:117], v[112:113]
	s_nop 0
	v_cvt_pk_bf16_f32 v122, v112, v113
	v_mul_f32_e32 v112, 0xbfb8aa3b, v118
	v_mul_f32_e32 v113, 0xbfb8aa3b, v119
	v_exp_f32_e32 v112, v112
	v_exp_f32_e32 v113, v113
	v_add_f32_e32 v112, 1.0, v112
	v_add_f32_e32 v113, 1.0, v113
	v_rcp_f32_e32 v112, v112
	v_rcp_f32_e32 v113, v113
	s_nop 0
	v_pk_mul_f32 v[112:113], v[118:119], v[112:113]
	s_nop 0
	v_pk_mul_f32 v[112:113], v[112:113], v[114:115]
	v_mul_f32_e32 v114, 0xbfb8aa3b, v108
	v_mul_f32_e32 v115, 0xbfb8aa3b, v109
	v_exp_f32_e32 v114, v114
	v_exp_f32_e32 v115, v115
	v_cvt_pk_bf16_f32 v123, v112, v113
	v_or_b32_e32 v112, 16, v146
	v_add_f32_e32 v114, 1.0, v114
	v_add_f32_e32 v115, 1.0, v115
	v_rcp_f32_e32 v114, v114
	v_rcp_f32_e32 v115, v115
	v_mad_i64_i32 v[112:113], s[12:13], v112, s81, v[138:139]
	v_lshl_add_u64 v[112:113], v[112:113], 0, v[140:141]
	v_pk_mul_f32 v[108:109], v[108:109], v[114:115]
	global_store_dwordx4 v[148:149], v[120:123], off sc1
	v_pk_mul_f32 v[104:105], v[108:109], v[104:105]
	s_nop 0
	v_cvt_pk_bf16_f32 v104, v104, v105
	v_mul_f32_e32 v105, 0xbfb8aa3b, v110
	v_exp_f32_e32 v105, v105
	s_nop 0
	v_add_f32_e32 v105, 1.0, v105
	v_rcp_f32_e32 v108, v105
	v_mul_f32_e32 v105, 0xbfb8aa3b, v111
	v_exp_f32_e32 v105, v105
	s_nop 0
	v_add_f32_e32 v105, 1.0, v105
	v_rcp_f32_e32 v109, v105
	s_nop 0
; __device__ __forceinline__ unsigned cvtpk(float lo, float hi) { const f32x2 v = (f32x2){lo, hi}; const bf16v2 b = __builtin_convertvector(v, bf16v2); return __builtin_bit_cast(unsigned, b); }
; __device__ __forceinline__ float siluf_(float x) { return x * sigmoidf_(x); }
;     __device__ __forceinline__ void operator()(const f32x4 (&acc)[2][2][4][2], const pg8::Unit& u, int wr, int wc, int fr, int fq) const {
;         const int row0 = u.pm * 256 + wr * 64 + fr, col0 = u.pn * 128 + wc * 32 + 8 * fq;
; #pragma unroll
;         for (int ai = 0; ai < 2; ++ai)
; #pragma unroll
;             for (int m = 0; m < 4; ++m) { bf16_t* rowp = O + (size_t)(row0 + ai * 128 + m * 16) * ldc + col0;
;                 const f32x4 g0 = acc[ai][0][m][0], g1 = acc[ai][0][m][1], u0 = acc[ai][1][m][0], u1 = acc[ai][1][m][1];
;                 u32x4 w; w.x = cvtpk(siluf_(g0[0]) * u0[0], siluf_(g0[1]) * u0[1]); w.y = cvtpk(siluf_(g0[2]) * u0[2], siluf_(g0[3]) * u0[3]);
;                 w.z = cvtpk(siluf_(g1[0]) * u1[0], siluf_(g1[1]) * u1[1]); w.w = cvtpk(siluf_(g1[2]) * u1[2], siluf_(g1[3]) * u1[3]);
;                 *(u32x4*)rowp = w; }
	v_pk_mul_f32 v[108:109], v[110:111], v[108:109]
	s_nop 0
	v_pk_mul_f32 v[106:107], v[108:109], v[106:107]
	s_nop 0
	v_cvt_pk_bf16_f32 v105, v106, v107
	v_mul_f32_e32 v106, 0xbfb8aa3b, v100
	v_mul_f32_e32 v107, 0xbfb8aa3b, v101
	v_exp_f32_e32 v106, v106
	v_exp_f32_e32 v107, v107
	v_add_f32_e32 v106, 1.0, v106
	v_add_f32_e32 v107, 1.0, v107
	v_rcp_f32_e32 v106, v106
	v_rcp_f32_e32 v107, v107
	s_nop 0
	v_pk_mul_f32 v[100:101], v[100:101], v[106:107]
	s_nop 0
	v_pk_mul_f32 v[96:97], v[100:101], v[96:97]
	s_nop 0
	v_cvt_pk_bf16_f32 v106, v96, v97
	v_mul_f32_e32 v96, 0xbfb8aa3b, v102
	v_mul_f32_e32 v97, 0xbfb8aa3b, v103
	v_exp_f32_e32 v96, v96
	v_exp_f32_e32 v97, v97
	v_add_f32_e32 v96, 1.0, v96
	v_add_f32_e32 v97, 1.0, v97
	v_rcp_f32_e32 v96, v96
	v_rcp_f32_e32 v97, v97
	s_nop 0
	v_pk_mul_f32 v[96:97], v[102:103], v[96:97]
	s_nop 0
	v_pk_mul_f32 v[96:97], v[96:97], v[98:99]
	v_mul_f32_e32 v98, 0xbfb8aa3b, v92
	v_mul_f32_e32 v99, 0xbfb8aa3b, v93
	v_exp_f32_e32 v98, v98
	v_exp_f32_e32 v99, v99
	v_cvt_pk_bf16_f32 v107, v96, v97
	v_or_b32_e32 v96, 32, v146
	v_add_f32_e32 v98, 1.0, v98
	v_add_f32_e32 v99, 1.0, v99
	v_rcp_f32_e32 v98, v98
	v_rcp_f32_e32 v99, v99
	v_mad_i64_i32 v[96:97], s[12:13], v96, s81, v[138:139]
	v_lshl_add_u64 v[96:97], v[96:97], 0, v[140:141]
	v_pk_mul_f32 v[92:93], v[92:93], v[98:99]
	global_store_dwordx4 v[112:113], v[104:107], off sc1
	v_pk_mul_f32 v[88:89], v[92:93], v[88:89]
	s_nop 0
	v_cvt_pk_bf16_f32 v88, v88, v89
	v_mul_f32_e32 v89, 0xbfb8aa3b, v94
	v_exp_f32_e32 v89, v89
	s_nop 0
	v_add_f32_e32 v89, 1.0, v89
	v_rcp_f32_e32 v92, v89
	v_mul_f32_e32 v89, 0xbfb8aa3b, v95
	v_exp_f32_e32 v89, v89
	s_nop 0
	v_add_f32_e32 v89, 1.0, v89
	v_rcp_f32_e32 v93, v89
	s_nop 0
	v_pk_mul_f32 v[92:93], v[94:95], v[92:93]
	s_nop 0
	v_pk_mul_f32 v[90:91], v[92:93], v[90:91]
	s_nop 0
	v_cvt_pk_bf16_f32 v89, v90, v91
	v_mul_f32_e32 v90, 0xbfb8aa3b, v84
	v_mul_f32_e32 v91, 0xbfb8aa3b, v85
	v_exp_f32_e32 v90, v90
	v_exp_f32_e32 v91, v91
	v_add_f32_e32 v90, 1.0, v90
	v_add_f32_e32 v91, 1.0, v91
	v_rcp_f32_e32 v90, v90
	v_rcp_f32_e32 v91, v91
	s_nop 0
	v_pk_mul_f32 v[84:85], v[84:85], v[90:91]
	s_nop 0
	v_pk_mul_f32 v[80:81], v[84:85], v[80:81]
	s_nop 0
	v_cvt_pk_bf16_f32 v90, v80, v81
	v_mul_f32_e32 v80, 0xbfb8aa3b, v86
	v_mul_f32_e32 v81, 0xbfb8aa3b, v87
	v_exp_f32_e32 v80, v80
	v_exp_f32_e32 v81, v81
	v_add_f32_e32 v80, 1.0, v80
	v_add_f32_e32 v81, 1.0, v81
	v_rcp_f32_e32 v80, v80
	v_rcp_f32_e32 v81, v81
	s_nop 0
	v_pk_mul_f32 v[80:81], v[86:87], v[80:81]
	s_nop 0
	v_pk_mul_f32 v[80:81], v[80:81], v[82:83]
	v_mul_f32_e32 v82, 0xbfb8aa3b, v76
	v_mul_f32_e32 v83, 0xbfb8aa3b, v77
	v_exp_f32_e32 v82, v82
	v_exp_f32_e32 v83, v83
	v_cvt_pk_bf16_f32 v91, v80, v81
	v_or_b32_e32 v80, 48, v146
	v_add_f32_e32 v82, 1.0, v82
	v_add_f32_e32 v83, 1.0, v83
	v_rcp_f32_e32 v82, v82
	v_rcp_f32_e32 v83, v83
	v_mad_i64_i32 v[80:81], s[12:13], v80, s81, v[138:139]
	v_lshl_add_u64 v[80:81], v[80:81], 0, v[140:141]
	v_pk_mul_f32 v[76:77], v[76:77], v[82:83]
	global_store_dwordx4 v[96:97], v[88:91], off sc1
	v_pk_mul_f32 v[72:73], v[76:77], v[72:73]
	s_nop 0
	v_cvt_pk_bf16_f32 v72, v72, v73
	v_mul_f32_e32 v73, 0xbfb8aa3b, v78
	v_exp_f32_e32 v73, v73
	s_nop 0
	v_add_f32_e32 v73, 1.0, v73
	v_rcp_f32_e32 v76, v73
	v_mul_f32_e32 v73, 0xbfb8aa3b, v79
	v_exp_f32_e32 v73, v73
	s_nop 0
	v_add_f32_e32 v73, 1.0, v73
	v_rcp_f32_e32 v77, v73
	s_nop 0
	v_pk_mul_f32 v[76:77], v[78:79], v[76:77]
	s_nop 0
	v_pk_mul_f32 v[74:75], v[76:77], v[74:75]
	s_nop 0
	v_cvt_pk_bf16_f32 v73, v74, v75
	v_mul_f32_e32 v74, 0xbfb8aa3b, v68
	v_mul_f32_e32 v75, 0xbfb8aa3b, v69
	v_exp_f32_e32 v74, v74
	v_exp_f32_e32 v75, v75
	v_add_f32_e32 v74, 1.0, v74
	v_add_f32_e32 v75, 1.0, v75
	v_rcp_f32_e32 v74, v74
	v_rcp_f32_e32 v75, v75
	s_nop 0
	v_pk_mul_f32 v[68:69], v[68:69], v[74:75]
	s_nop 0
	v_pk_mul_f32 v[64:65], v[68:69], v[64:65]
	s_nop 0
	v_cvt_pk_bf16_f32 v74, v64, v65
	v_mul_f32_e32 v64, 0xbfb8aa3b, v70
	v_mul_f32_e32 v65, 0xbfb8aa3b, v71
	v_exp_f32_e32 v64, v64
	v_exp_f32_e32 v65, v65
	v_add_f32_e32 v64, 1.0, v64
	v_add_f32_e32 v65, 1.0, v65
	v_rcp_f32_e32 v64, v64
	v_rcp_f32_e32 v65, v65
	s_nop 0
	v_pk_mul_f32 v[64:65], v[70:71], v[64:65]
	s_nop 0
	v_pk_mul_f32 v[64:65], v[64:65], v[66:67]
	v_mul_f32_e32 v66, 0xbfb8aa3b, v60
	v_mul_f32_e32 v67, 0xbfb8aa3b, v61
	v_exp_f32_e32 v66, v66
	v_exp_f32_e32 v67, v67
	v_cvt_pk_bf16_f32 v75, v64, v65
	v_add_u32_e32 v64, 0x80, v146
	v_add_f32_e32 v66, 1.0, v66
	v_add_f32_e32 v67, 1.0, v67
	v_rcp_f32_e32 v66, v66
	v_rcp_f32_e32 v67, v67
	v_mad_i64_i32 v[64:65], s[12:13], v64, s81, v[138:139]
	v_lshl_add_u64 v[64:65], v[64:65], 0, v[140:141]
	v_pk_mul_f32 v[60:61], v[60:61], v[66:67]
	global_store_dwordx4 v[80:81], v[72:75], off sc1
	v_pk_mul_f32 v[56:57], v[60:61], v[56:57]
	s_nop 0
	v_cvt_pk_bf16_f32 v56, v56, v57
	v_mul_f32_e32 v57, 0xbfb8aa3b, v62
	v_exp_f32_e32 v57, v57
	s_nop 0
	v_add_f32_e32 v57, 1.0, v57
	v_rcp_f32_e32 v60, v57
	v_mul_f32_e32 v57, 0xbfb8aa3b, v63
	v_exp_f32_e32 v57, v57
	s_nop 0
	v_add_f32_e32 v57, 1.0, v57
	v_rcp_f32_e32 v61, v57
	s_nop 0
	v_pk_mul_f32 v[60:61], v[62:63], v[60:61]
	s_nop 0
	v_pk_mul_f32 v[58:59], v[60:61], v[58:59]
	s_nop 0
	v_cvt_pk_bf16_f32 v57, v58, v59
	v_mul_f32_e32 v58, 0xbfb8aa3b, v52
	v_mul_f32_e32 v59, 0xbfb8aa3b, v53
	v_exp_f32_e32 v58, v58
	v_exp_f32_e32 v59, v59
	v_add_f32_e32 v58, 1.0, v58
	v_add_f32_e32 v59, 1.0, v59
	v_rcp_f32_e32 v58, v58
	v_rcp_f32_e32 v59, v59
	s_nop 0
	v_pk_mul_f32 v[52:53], v[52:53], v[58:59]
	s_nop 0
	v_pk_mul_f32 v[48:49], v[52:53], v[48:49]
	s_nop 0
	v_cvt_pk_bf16_f32 v58, v48, v49
; __device__ __forceinline__ unsigned cvtpk(float lo, float hi) { const f32x2 v = (f32x2){lo, hi}; const bf16v2 b = __builtin_convertvector(v, bf16v2); return __builtin_bit_cast(unsigned, b); }
; __device__ __forceinline__ float siluf_(float x) { return x * sigmoidf_(x); }
;     __device__ __forceinline__ void operator()(const f32x4 (&acc)[2][2][4][2], const pg8::Unit& u, int wr, int wc, int fr, int fq) const {
;         const int row0 = u.pm * 256 + wr * 64 + fr, col0 = u.pn * 128 + wc * 32 + 8 * fq;
; #pragma unroll
;         for (int ai = 0; ai < 2; ++ai)
; #pragma unroll
;             for (int m = 0; m < 4; ++m) { bf16_t* rowp = O + (size_t)(row0 + ai * 128 + m * 16) * ldc + col0;
;                 const f32x4 g0 = acc[ai][0][m][0], g1 = acc[ai][0][m][1], u0 = acc[ai][1][m][0], u1 = acc[ai][1][m][1];
;                 u32x4 w; w.x = cvtpk(siluf_(g0[0]) * u0[0], siluf_(g0[1]) * u0[1]); w.y = cvtpk(siluf_(g0[2]) * u0[2], siluf_(g0[3]) * u0[3]);
;                 w.z = cvtpk(siluf_(g1[0]) * u1[0], siluf_(g1[1]) * u1[1]); w.w = cvtpk(siluf_(g1[2]) * u1[2], siluf_(g1[3]) * u1[3]);
;                 *(u32x4*)rowp = w; }
	v_mul_f32_e32 v48, 0xbfb8aa3b, v54
	v_mul_f32_e32 v49, 0xbfb8aa3b, v55
	v_exp_f32_e32 v48, v48
	v_exp_f32_e32 v49, v49
	v_add_f32_e32 v48, 1.0, v48
	v_add_f32_e32 v49, 1.0, v49
	v_rcp_f32_e32 v48, v48
	v_rcp_f32_e32 v49, v49
	s_nop 0
	v_pk_mul_f32 v[48:49], v[54:55], v[48:49]
	s_nop 0
	v_pk_mul_f32 v[48:49], v[48:49], v[50:51]
	v_mul_f32_e32 v50, 0xbfb8aa3b, v44
	v_mul_f32_e32 v51, 0xbfb8aa3b, v45
	v_exp_f32_e32 v50, v50
	v_exp_f32_e32 v51, v51
	v_cvt_pk_bf16_f32 v59, v48, v49
	v_add_u32_e32 v48, 0x90, v146
	v_add_f32_e32 v50, 1.0, v50
	v_add_f32_e32 v51, 1.0, v51
	v_rcp_f32_e32 v50, v50
	v_rcp_f32_e32 v51, v51
	v_mad_i64_i32 v[48:49], s[12:13], v48, s81, v[138:139]
	v_lshl_add_u64 v[48:49], v[48:49], 0, v[140:141]
	v_pk_mul_f32 v[44:45], v[44:45], v[50:51]
	global_store_dwordx4 v[64:65], v[56:59], off sc1
	v_pk_mul_f32 v[40:41], v[44:45], v[40:41]
	s_nop 0
	v_cvt_pk_bf16_f32 v40, v40, v41
	v_mul_f32_e32 v41, 0xbfb8aa3b, v46
	v_exp_f32_e32 v41, v41
	s_nop 0
	v_add_f32_e32 v41, 1.0, v41
	v_rcp_f32_e32 v44, v41
	v_mul_f32_e32 v41, 0xbfb8aa3b, v47
	v_exp_f32_e32 v41, v41
	s_nop 0
	v_add_f32_e32 v41, 1.0, v41
	v_rcp_f32_e32 v45, v41
	s_nop 0
	v_pk_mul_f32 v[44:45], v[46:47], v[44:45]
	s_nop 0
	v_pk_mul_f32 v[42:43], v[44:45], v[42:43]
	s_nop 0
	v_cvt_pk_bf16_f32 v41, v42, v43
	v_mul_f32_e32 v42, 0xbfb8aa3b, v36
	v_mul_f32_e32 v43, 0xbfb8aa3b, v37
	v_exp_f32_e32 v42, v42
	v_exp_f32_e32 v43, v43
	v_add_f32_e32 v42, 1.0, v42
	v_add_f32_e32 v43, 1.0, v43
	v_rcp_f32_e32 v42, v42
	v_rcp_f32_e32 v43, v43
	s_nop 0
	v_pk_mul_f32 v[36:37], v[36:37], v[42:43]
	s_nop 0
	v_pk_mul_f32 v[32:33], v[36:37], v[32:33]
	s_nop 0
	v_cvt_pk_bf16_f32 v42, v32, v33
	v_mul_f32_e32 v32, 0xbfb8aa3b, v38
	v_mul_f32_e32 v33, 0xbfb8aa3b, v39
	v_exp_f32_e32 v32, v32
	v_exp_f32_e32 v33, v33
	v_add_f32_e32 v32, 1.0, v32
	v_add_f32_e32 v33, 1.0, v33
	v_rcp_f32_e32 v32, v32
	v_rcp_f32_e32 v33, v33
	s_nop 0
	v_pk_mul_f32 v[32:33], v[38:39], v[32:33]
	s_nop 0
	v_pk_mul_f32 v[32:33], v[32:33], v[34:35]
	v_mul_f32_e32 v34, 0xbfb8aa3b, v28
	v_mul_f32_e32 v35, 0xbfb8aa3b, v29
	v_exp_f32_e32 v34, v34
	v_exp_f32_e32 v35, v35
	v_cvt_pk_bf16_f32 v43, v32, v33
	v_add_u32_e32 v32, 0xa0, v146
	v_add_f32_e32 v34, 1.0, v34
	v_add_f32_e32 v35, 1.0, v35
	v_rcp_f32_e32 v34, v34
	v_rcp_f32_e32 v35, v35
	v_mad_i64_i32 v[32:33], s[12:13], v32, s81, v[138:139]
	v_lshl_add_u64 v[32:33], v[32:33], 0, v[140:141]
	v_pk_mul_f32 v[28:29], v[28:29], v[34:35]
	global_store_dwordx4 v[48:49], v[40:43], off sc1
	v_pk_mul_f32 v[24:25], v[28:29], v[24:25]
	s_nop 0
	v_cvt_pk_bf16_f32 v24, v24, v25
	v_mul_f32_e32 v25, 0xbfb8aa3b, v30
	v_exp_f32_e32 v25, v25
	s_nop 0
	v_add_f32_e32 v25, 1.0, v25
	v_rcp_f32_e32 v28, v25
	v_mul_f32_e32 v25, 0xbfb8aa3b, v31
	v_exp_f32_e32 v25, v25
	s_nop 0
	v_add_f32_e32 v25, 1.0, v25
	v_rcp_f32_e32 v29, v25
	s_nop 0
	v_pk_mul_f32 v[28:29], v[30:31], v[28:29]
	s_nop 0
	v_pk_mul_f32 v[26:27], v[28:29], v[26:27]
	s_nop 0
	v_cvt_pk_bf16_f32 v25, v26, v27
	v_mul_f32_e32 v26, 0xbfb8aa3b, v20
	v_mul_f32_e32 v27, 0xbfb8aa3b, v21
	v_exp_f32_e32 v26, v26
	v_exp_f32_e32 v27, v27
	v_add_f32_e32 v26, 1.0, v26
	v_add_f32_e32 v27, 1.0, v27
	v_rcp_f32_e32 v26, v26
	v_rcp_f32_e32 v27, v27
	s_nop 0
	v_pk_mul_f32 v[20:21], v[20:21], v[26:27]
	s_nop 0
	v_pk_mul_f32 v[16:17], v[20:21], v[16:17]
	s_nop 0
	v_cvt_pk_bf16_f32 v26, v16, v17
	v_mul_f32_e32 v16, 0xbfb8aa3b, v22
	v_mul_f32_e32 v17, 0xbfb8aa3b, v23
	v_exp_f32_e32 v16, v16
	v_exp_f32_e32 v17, v17
	v_add_f32_e32 v16, 1.0, v16
	v_add_f32_e32 v17, 1.0, v17
	v_rcp_f32_e32 v16, v16
	v_rcp_f32_e32 v17, v17
	s_nop 0
	v_pk_mul_f32 v[16:17], v[22:23], v[16:17]
	s_nop 0
	v_pk_mul_f32 v[16:17], v[16:17], v[18:19]
	v_mul_f32_e32 v18, 0xbfb8aa3b, v12
	v_mul_f32_e32 v19, 0xbfb8aa3b, v13
	v_exp_f32_e32 v18, v18
	v_exp_f32_e32 v19, v19
	v_cvt_pk_bf16_f32 v27, v16, v17
	v_add_u32_e32 v16, 0xb0, v146
	v_add_f32_e32 v18, 1.0, v18
	v_add_f32_e32 v19, 1.0, v19
	v_rcp_f32_e32 v18, v18
	v_rcp_f32_e32 v19, v19
	v_mad_i64_i32 v[16:17], s[12:13], v16, s81, v[138:139]
	v_lshl_add_u64 v[16:17], v[16:17], 0, v[140:141]
	v_pk_mul_f32 v[12:13], v[12:13], v[18:19]
	s_mov_b64 s[12:13], s[6:7]
	v_pk_mul_f32 v[8:9], v[12:13], v[8:9]
	global_store_dwordx4 v[32:33], v[24:27], off sc1
	v_cvt_pk_bf16_f32 v8, v8, v9
	v_mul_f32_e32 v9, 0xbfb8aa3b, v14
	v_exp_f32_e32 v9, v9
	s_nop 0
	v_add_f32_e32 v9, 1.0, v9
	v_rcp_f32_e32 v12, v9
	v_mul_f32_e32 v9, 0xbfb8aa3b, v15
	v_exp_f32_e32 v9, v9
	s_nop 0
	v_add_f32_e32 v9, 1.0, v9
	v_rcp_f32_e32 v13, v9
	s_nop 0
	v_pk_mul_f32 v[12:13], v[14:15], v[12:13]
	s_nop 0
	v_pk_mul_f32 v[10:11], v[12:13], v[10:11]
	s_nop 0
	v_cvt_pk_bf16_f32 v9, v10, v11
	v_mul_f32_e32 v10, 0xbfb8aa3b, v4
	v_mul_f32_e32 v11, 0xbfb8aa3b, v5
	v_exp_f32_e32 v10, v10
	v_exp_f32_e32 v11, v11
	v_add_f32_e32 v10, 1.0, v10
	v_add_f32_e32 v11, 1.0, v11
	v_rcp_f32_e32 v10, v10
	v_rcp_f32_e32 v11, v11
	s_nop 0
	v_pk_mul_f32 v[4:5], v[4:5], v[10:11]
	s_nop 0
	v_pk_mul_f32 v[0:1], v[4:5], v[0:1]
	s_nop 0
	v_cvt_pk_bf16_f32 v10, v0, v1
	v_mul_f32_e32 v0, 0xbfb8aa3b, v6
	v_mul_f32_e32 v1, 0xbfb8aa3b, v7
	v_exp_f32_e32 v0, v0
	v_exp_f32_e32 v1, v1
	v_add_f32_e32 v0, 1.0, v0
	v_add_f32_e32 v1, 1.0, v1
	v_rcp_f32_e32 v0, v0
	v_rcp_f32_e32 v1, v1
	s_nop 0
	v_pk_mul_f32 v[0:1], v[6:7], v[0:1]
	s_nop 0
	v_pk_mul_f32 v[0:1], v[0:1], v[2:3]
	s_nop 0
	v_cvt_pk_bf16_f32 v11, v0, v1
	global_store_dwordx4 v[16:17], v[8:11], off sc1
	s_cbranch_vccz .LBB0_111
	s_waitcnt vmcnt(0)
	v_readlane_b32 s22, v255, 14
	s_cmpk_gt_u32 s19, 0xff
	v_readlane_b32 s23, v255, 15
	s_mov_b64 s[28:29], s[54:55]
	s_cbranch_scc1 .LBB0_118
	s_barrier

; __device__ __forceinline__ unsigned cvtpk(float lo, float hi) { const f32x2 v = (f32x2){lo, hi}; const bf16v2 b = __builtin_convertvector(v, bf16v2); return __builtin_bit_cast(unsigned, b); }
; __device__ void phase_rowprep(const float* xsrc, const bf16_t* __restrict__ m, const float* __restrict__ gpost, float* xdst, const float* __restrict__ gpre, bf16_t* __restrict__ hdst) {
;     ...
;         if (hdst) {
;             float ss = 0.f;
; #pragma unroll
;             for (int i = 0; i < 4; ++i) ss += xv[i][0] * xv[i][0] + xv[i][1] * xv[i][1] + xv[i][2] * xv[i][2] + xv[i][3] * xv[i][3];
; #pragma unroll
;             for (int o = 32; o >= 1; o >>= 1) ss += __shfl_xor(ss, o);
;             const float rs = rsqrtf(ss * (1.0f / D) + EPS);
; #pragma unroll
;             for (int i = 0; i < 4; ++i) { const f32x4 hv = xv[i] * rs * gq[i]; *(u32x2*)(hdst + (size_t)row * D + i * 256 + lane * 4) = (u32x2){cvtpk(hv[0], hv[1]), cvtpk(hv[2], hv[3])}; }
;         }
;         row = nrow;
.LBB0_123:
	v_mov_b32_e32 v86, v45
	v_mov_b32_e32 v87, v41
	v_mov_b32_e32 v84, v44
	v_mov_b32_e32 v85, v40
	v_pk_mul_f32 v[86:87], v[86:87], v[86:87]
	v_mov_b32_e32 v88, v33
	v_pk_fma_f32 v[84:85], v[84:85], v[84:85], v[86:87]
	v_mov_b32_e32 v86, v46
	v_mov_b32_e32 v87, v42
	v_pk_fma_f32 v[84:85], v[86:87], v[86:87], v[84:85]
	v_mov_b32_e32 v86, v47
	v_mov_b32_e32 v87, v43
	v_mov_b32_e32 v89, v37
	v_pk_fma_f32 v[84:85], v[86:87], v[86:87], v[84:85]
	v_mov_b32_e32 v86, v32
	v_mov_b32_e32 v87, v36
	v_pk_mul_f32 v[88:89], v[88:89], v[88:89]
	v_add_f32_e32 v84, v84, v85
	v_pk_fma_f32 v[86:87], v[86:87], v[86:87], v[88:89]
	v_mov_b32_e32 v88, v34
	v_mov_b32_e32 v89, v38
	v_pk_fma_f32 v[86:87], v[88:89], v[88:89], v[86:87]
	v_mov_b32_e32 v88, v35
	v_mov_b32_e32 v89, v39
	v_pk_fma_f32 v[86:87], v[88:89], v[88:89], v[86:87]
	s_and_b64 s[0:1], exec, s[0:1]
	v_add_f32_e32 v84, v87, v84
	v_add_f32_e32 v84, v86, v84
	ds_bpermute_b32 v85, v65, v84
	v_lshl_add_u64 v[86:87], v[66:67], 0, v[176:177]
	s_or_b64 s[12:13], s[0:1], s[12:13]
	v_lshl_add_u64 v[66:67], v[66:67], 0, s[8:9]
	v_lshl_add_u64 v[70:71], v[70:71], 0, s[10:11]
	s_waitcnt lgkmcnt(0)
	v_add_f32_e32 v84, v84, v85
	ds_bpermute_b32 v85, v92, v84
	v_lshl_add_u64 v[72:73], v[72:73], 0, s[10:11]
	v_lshl_add_u64 v[74:75], v[74:75], 0, s[8:9]
	s_waitcnt vmcnt(3)
	v_mov_b64_e32 v[90:91], v[76:77]
	s_waitcnt vmcnt(2)
	v_mov_b64_e32 v[88:89], v[78:79]
	s_waitcnt lgkmcnt(0)
	v_add_f32_e32 v84, v84, v85
	ds_bpermute_b32 v85, v93, v84
	s_waitcnt lgkmcnt(0)
	v_add_f32_e32 v84, v84, v85
	ds_bpermute_b32 v85, v94, v84
	s_waitcnt lgkmcnt(0)
	v_add_f32_e32 v84, v84, v85
	ds_bpermute_b32 v85, v95, v84
	s_waitcnt lgkmcnt(0)
	v_add_f32_e32 v84, v84, v85
	ds_bpermute_b32 v85, v96, v84
	s_waitcnt lgkmcnt(0)
	v_add_f32_e32 v84, v84, v85
	v_fmamk_f32 v84, v84, 0x3a800000, v225
	v_cmp_gt_f32_e32 vcc, s25, v84
	v_mul_f32_e32 v85, 0x4b800000, v84
	s_nop 0
	v_cndmask_b32_e32 v84, v84, v85, vcc
	v_rsq_f32_e32 v84, v84
	s_nop 0
	v_mul_f32_e32 v85, 0x45800000, v84
	v_cndmask_b32_e32 v84, v84, v85, vcc
	v_pk_mul_f32 v[44:45], v[44:45], v[84:85] op_sel_hi:[1,0]
	v_pk_mul_f32 v[46:47], v[46:47], v[84:85] op_sel_hi:[1,0]
	v_pk_mul_f32 v[44:45], v[4:5], v[44:45]
	v_pk_mul_f32 v[46:47], v[6:7], v[46:47]
	v_pk_mul_f32 v[40:41], v[40:41], v[84:85] op_sel_hi:[1,0]
	v_pk_mul_f32 v[42:43], v[42:43], v[84:85] op_sel_hi:[1,0]
	v_pk_mul_f32 v[36:37], v[36:37], v[84:85] op_sel_hi:[1,0]
	v_pk_mul_f32 v[38:39], v[38:39], v[84:85] op_sel_hi:[1,0]
	v_pk_mul_f32 v[32:33], v[32:33], v[84:85] op_sel_hi:[1,0]
	v_pk_mul_f32 v[34:35], v[34:35], v[84:85] op_sel_hi:[1,0]
	v_cvt_pk_bf16_f32 v44, v44, v45
	v_cvt_pk_bf16_f32 v45, v46, v47
	v_add_co_u32_e32 v46, vcc, s83, v86
	v_pk_mul_f32 v[42:43], v[14:15], v[42:43]
	v_pk_mul_f32 v[40:41], v[12:13], v[40:41]
	v_pk_mul_f32 v[38:39], v[22:23], v[38:39]
	v_pk_mul_f32 v[36:37], v[20:21], v[36:37]
	v_pk_mul_f32 v[34:35], v[30:31], v[34:35]
	v_pk_mul_f32 v[32:33], v[28:29], v[32:33]
	v_addc_co_u32_e32 v47, vcc, 0, v87, vcc
	v_cvt_pk_bf16_f32 v40, v40, v41
	v_cvt_pk_bf16_f32 v41, v42, v43
	v_cvt_pk_bf16_f32 v36, v36, v37
	v_cvt_pk_bf16_f32 v37, v38, v39
	v_cvt_pk_bf16_f32 v32, v32, v33
	v_cvt_pk_bf16_f32 v33, v34, v35
	global_store_dwordx2 v[46:47], v[44:45], off sc1
	global_store_dwordx2 v[46:47], v[40:41], off offset:512 sc1
	global_store_dwordx2 v[46:47], v[36:37], off offset:1024 sc1
	global_store_dwordx2 v[46:47], v[32:33], off offset:1536 sc1
	v_mov_b64_e32 v[44:45], v[48:49]
	v_mov_b64_e32 v[40:41], v[52:53]
	v_mov_b64_e32 v[36:37], v[56:57]
	v_mov_b64_e32 v[32:33], v[60:61]
	s_waitcnt vmcnt(5)
	v_mov_b64_e32 v[86:87], v[80:81]
	s_waitcnt vmcnt(4)
	v_mov_b64_e32 v[84:85], v[82:83]
	v_mov_b64_e32 v[46:47], v[50:51]
	v_mov_b64_e32 v[42:43], v[54:55]
	v_mov_b64_e32 v[38:39], v[58:59]
	v_mov_b64_e32 v[34:35], v[62:63]
	s_andn2_b64 exec, exec, s[12:13]
	s_cbranch_execz .LBB0_128

; #define PG8_STAGE(bufoff, gbase, voff) do { _Pragma("unroll") for (int _i = 0; _i < 2; ++_i) \
;         __builtin_amdgcn_global_load_lds((const unsigned*)((const char*)(gbase) + (voff)[_i]), (PG8_LAS unsigned*)(lds + (bufoff) + ldsw + _i * 8192), 16, 0, 0); } while (0)
; #define PG8_LDA(dst, b, h) do { _Pragma("unroll") for (int m = 0; m < 4; ++m) _Pragma("unroll") for (int k = 0; k < 2; ++k) dst[m][k] = *(const PG8_LAS bf16x8*)(lds + PG8_SA(b, h) + aoff + m * 2048 + k * 1024); } while (0)
; #define PG8_LDB(dst, b, h) do { _Pragma("unroll") for (int n = 0; n < 2; ++n) _Pragma("unroll") for (int k = 0; k < 2; ++k) dst[n][k] = *(const PG8_LAS bf16x8*)(lds + PG8_SB(b, h) + boff + n * 2048 + k * 1024); } while (0)
; #define PG8_MMA(ai, bj, At, Bt) do { __builtin_amdgcn_s_setprio(1); _Pragma("unroll") for (int m = 0; m < 4; ++m) _Pragma("unroll") for (int n = 0; n < 2; ++n) _Pragma("unroll") for (int k = 0; k < 2; ++k) \
;         acc[ai][bj][m][n] = __builtin_amdgcn_mfma_f32_16x16x32_bf16(Bt[n][k], At[m][k], acc[ai][bj][m][n], 0, 0, 0); __builtin_amdgcn_s_setprio(0); } while (0)
; #define PG8_WAIT_V(n) asm volatile("s_waitcnt vmcnt(" #n ")" ::: "memory")
; #define PG8_WAIT_L(n) asm volatile("s_waitcnt lgkmcnt(" #n ")" ::: "memory")
; #define PG8_BAR __builtin_amdgcn_s_barrier()
; #define PG8_SCHED __builtin_amdgcn_sched_barrier(0)
; template <class Epi, class Sched>
; __device__ __forceinline__ void gemm_phase(PG8_LAS unsigned char* lds, const Gemm g, const Sched& S, const Epi& E) {
;     ...
;             PG8_LDB(B0, 0, 0); PG8_SCHED; PG8_LDA(At, 0, 0); PG8_STAGE(PG8_SA(1, 1), a1 + hstep, voffA);
;             PG8_WAIT_L(8); PG8_BAR; PG8_WAIT_L(0); PG8_MMA(0, 0, At, B0); PG8_BAR; PG8_SCHED;
;             PG8_LDB(B1, 0, 1); PG8_STAGE(PG8_SB(0, 0), b2, voffB);
;             PG8_BAR; PG8_WAIT_L(0); PG8_MMA(0, 1, At, B1); PG8_BAR;
;             PG8_LDA(At, 0, 1); PG8_STAGE(PG8_SA(0, 0), a2, voffA);
;             PG8_BAR; PG8_WAIT_L(0); PG8_MMA(1, 0, At, B0); PG8_BAR; PG8_SCHED;
;             PG8_STAGE(PG8_SB(0, 1), b2 + hstep, voffB);
;             PG8_WAIT_V(6); PG8_BAR; PG8_MMA(1, 1, At, B1); PG8_BAR;
.LBB0_137:
	s_add_u32 s14, s12, 0xfffc0080
	s_addc_u32 s15, s13, -1
	v_add_u32_e32 v154, 0x10000, v139
	ds_read_b128 v[142:145], v154
	ds_read_b128 v[146:149], v154 offset:1024
	ds_read_b128 v[150:153], v154 offset:2048
	ds_read_b128 v[154:157], v154 offset:3072
	s_cmp_eq_u32 s45, 12
	s_cselect_b32 s17, s7, s15
	s_cselect_b32 s16, s40, s14
	s_cselect_b32 s15, s5, s44
	s_cselect_b32 s14, s41, s43
	s_add_i32 m0, s1, 0xc000
	ds_read_b128 v[158:161], v141
	ds_read_b128 v[162:165], v141 offset:1024
	ds_read_b128 v[166:169], v141 offset:2048
	ds_read_b128 v[170:173], v141 offset:3072
	ds_read_b128 v[178:181], v141 offset:4096
	ds_read_b128 v[182:185], v141 offset:5120
	ds_read_b128 v[186:189], v141 offset:6144
	global_load_lds_dwordx4 v134, s[12:13]
	s_add_i32 m0, s1, 0xe000
	ds_read_b128 v[190:193], v141 offset:7168
	global_load_lds_dwordx4 v136, s[12:13]
	s_waitcnt lgkmcnt(8)
	s_barrier
	s_waitcnt lgkmcnt(7)
	v_mfma_f32_16x16x32_bf16 v[124:127], v[142:145], v[158:161], v[124:127]
	v_mfma_f32_16x16x32_bf16 v[120:123], v[150:153], v[158:161], v[120:123]
	s_waitcnt lgkmcnt(5)
	v_mfma_f32_16x16x32_bf16 v[116:119], v[142:145], v[166:169], v[116:119]
	v_mfma_f32_16x16x32_bf16 v[112:115], v[150:153], v[166:169], v[112:115]
	s_waitcnt lgkmcnt(3)
	v_mfma_f32_16x16x32_bf16 v[100:103], v[142:145], v[178:181], v[100:103]
	v_mfma_f32_16x16x32_bf16 v[96:99], v[150:153], v[178:181], v[96:99]
	s_waitcnt lgkmcnt(1)
	v_mfma_f32_16x16x32_bf16 v[84:87], v[142:145], v[186:189], v[84:87]
	v_mfma_f32_16x16x32_bf16 v[80:83], v[150:153], v[186:189], v[80:83]
	v_mfma_f32_16x16x32_bf16 v[124:127], v[146:149], v[162:165], v[124:127]
	v_mfma_f32_16x16x32_bf16 v[120:123], v[154:157], v[162:165], v[120:123]
	v_mfma_f32_16x16x32_bf16 v[116:119], v[146:149], v[170:173], v[116:119]
	v_mfma_f32_16x16x32_bf16 v[112:115], v[154:157], v[170:173], v[112:115]
	v_mfma_f32_16x16x32_bf16 v[100:103], v[146:149], v[182:185], v[100:103]
	v_mfma_f32_16x16x32_bf16 v[96:99], v[154:157], v[182:185], v[96:99]
	s_waitcnt lgkmcnt(0)
	v_mfma_f32_16x16x32_bf16 v[84:87], v[146:149], v[190:193], v[84:87]
	v_mfma_f32_16x16x32_bf16 v[80:83], v[154:157], v[190:193], v[80:83]
	s_barrier
	s_add_i32 s48, 0, 0x14000
	v_add_u32_e32 v174, 0x14000, v139
	ds_read_b128 v[194:197], v174
	ds_read_b128 v[198:201], v174 offset:1024
	s_add_u32 s98, s14, 0x80
	s_addc_u32 s99, s15, 0
	s_add_i32 m0, s20, 0x10000
	ds_read_b128 v[202:205], v174 offset:2048
	global_load_lds_dwordx4 v176, s[14:15]
	s_add_i32 m0, s20, 0x12000
	ds_read_b128 v[206:209], v174 offset:3072
	global_load_lds_dwordx4 v128, s[14:15]
	s_barrier
	s_waitcnt lgkmcnt(3)
	v_mfma_f32_16x16x32_bf16 v[108:111], v[194:197], v[158:161], v[108:111]
	s_waitcnt lgkmcnt(1)
	v_mfma_f32_16x16x32_bf16 v[104:107], v[202:205], v[158:161], v[104:107]
	v_mfma_f32_16x16x32_bf16 v[92:95], v[194:197], v[166:169], v[92:95]
	v_mfma_f32_16x16x32_bf16 v[88:91], v[202:205], v[166:169], v[88:91]
	v_mfma_f32_16x16x32_bf16 v[76:79], v[194:197], v[178:181], v[76:79]
	v_mfma_f32_16x16x32_bf16 v[72:75], v[202:205], v[178:181], v[72:75]
	v_mfma_f32_16x16x32_bf16 v[68:71], v[194:197], v[186:189], v[68:71]
	v_mfma_f32_16x16x32_bf16 v[64:67], v[202:205], v[186:189], v[64:67]
	v_mfma_f32_16x16x32_bf16 v[108:111], v[198:201], v[162:165], v[108:111]
	s_waitcnt lgkmcnt(0)
	v_mfma_f32_16x16x32_bf16 v[104:107], v[206:209], v[162:165], v[104:107]
	v_mfma_f32_16x16x32_bf16 v[92:95], v[198:201], v[170:173], v[92:95]
	v_mfma_f32_16x16x32_bf16 v[88:91], v[206:209], v[170:173], v[88:91]
	v_mfma_f32_16x16x32_bf16 v[76:79], v[198:201], v[182:185], v[76:79]
	v_mfma_f32_16x16x32_bf16 v[72:75], v[206:209], v[182:185], v[72:75]
	v_mfma_f32_16x16x32_bf16 v[68:71], v[198:201], v[190:193], v[68:71]
	v_mfma_f32_16x16x32_bf16 v[64:67], v[206:209], v[190:193], v[64:67]
	s_mov_b32 m0, s1
	s_add_u32 s100, s16, 0x80
	s_addc_u32 s101, s17, 0
	s_barrier
	ds_read_b128 v[158:161], v141 offset:16384
	ds_read_b128 v[162:165], v141 offset:17408
	ds_read_b128 v[166:169], v141 offset:18432
	ds_read_b128 v[170:173], v141 offset:19456
	ds_read_b128 v[178:181], v141 offset:20480
	ds_read_b128 v[182:185], v141 offset:21504
	ds_read_b128 v[186:189], v141 offset:22528
	global_load_lds_dwordx4 v132, s[16:17]
	s_mov_b32 m0, s22
	ds_read_b128 v[190:193], v141 offset:23552
	global_load_lds_dwordx4 v130, s[16:17]
	s_barrier
	s_waitcnt lgkmcnt(7)
	v_mfma_f32_16x16x32_bf16 v[60:63], v[142:145], v[158:161], v[60:63]
	v_mfma_f32_16x16x32_bf16 v[56:59], v[150:153], v[158:161], v[56:59]
	s_waitcnt lgkmcnt(5)
	v_mfma_f32_16x16x32_bf16 v[52:55], v[142:145], v[166:169], v[52:55]
	v_mfma_f32_16x16x32_bf16 v[48:51], v[150:153], v[166:169], v[48:51]
	s_waitcnt lgkmcnt(3)
	v_mfma_f32_16x16x32_bf16 v[36:39], v[142:145], v[178:181], v[36:39]
	v_mfma_f32_16x16x32_bf16 v[32:35], v[150:153], v[178:181], v[32:35]
	s_waitcnt lgkmcnt(1)
	v_mfma_f32_16x16x32_bf16 v[20:23], v[142:145], v[186:189], v[20:23]
	v_mfma_f32_16x16x32_bf16 v[16:19], v[150:153], v[186:189], v[16:19]
	v_mfma_f32_16x16x32_bf16 v[60:63], v[146:149], v[162:165], v[60:63]
	v_mfma_f32_16x16x32_bf16 v[56:59], v[154:157], v[162:165], v[56:59]
	v_mfma_f32_16x16x32_bf16 v[52:55], v[146:149], v[170:173], v[52:55]
	v_mfma_f32_16x16x32_bf16 v[48:51], v[154:157], v[170:173], v[48:51]
	v_mfma_f32_16x16x32_bf16 v[36:39], v[146:149], v[182:185], v[36:39]
	v_mfma_f32_16x16x32_bf16 v[32:35], v[154:157], v[182:185], v[32:35]
	s_waitcnt lgkmcnt(0)
	v_mfma_f32_16x16x32_bf16 v[20:23], v[146:149], v[190:193], v[20:23]
	v_mfma_f32_16x16x32_bf16 v[16:19], v[154:157], v[190:193], v[16:19]
	s_barrier
; #define PG8_STAGE(bufoff, gbase, voff) do { _Pragma("unroll") for (int _i = 0; _i < 2; ++_i) \
;         __builtin_amdgcn_global_load_lds((const unsigned*)((const char*)(gbase) + (voff)[_i]), (PG8_LAS unsigned*)(lds + (bufoff) + ldsw + _i * 8192), 16, 0, 0); } while (0)
; #define PG8_LDA(dst, b, h) do { _Pragma("unroll") for (int m = 0; m < 4; ++m) _Pragma("unroll") for (int k = 0; k < 2; ++k) dst[m][k] = *(const PG8_LAS bf16x8*)(lds + PG8_SA(b, h) + aoff + m * 2048 + k * 1024); } while (0)
; #define PG8_LDB(dst, b, h) do { _Pragma("unroll") for (int n = 0; n < 2; ++n) _Pragma("unroll") for (int k = 0; k < 2; ++k) dst[n][k] = *(const PG8_LAS bf16x8*)(lds + PG8_SB(b, h) + boff + n * 2048 + k * 1024); } while (0)
; #define PG8_MMA(ai, bj, At, Bt) do { __builtin_amdgcn_s_setprio(1); _Pragma("unroll") for (int m = 0; m < 4; ++m) _Pragma("unroll") for (int n = 0; n < 2; ++n) _Pragma("unroll") for (int k = 0; k < 2; ++k) \
;         acc[ai][bj][m][n] = __builtin_amdgcn_mfma_f32_16x16x32_bf16(Bt[n][k], At[m][k], acc[ai][bj][m][n], 0, 0, 0); __builtin_amdgcn_s_setprio(0); } while (0)
; #define PG8_WAIT_V(n) asm volatile("s_waitcnt vmcnt(" #n ")" ::: "memory")
; #define PG8_WAIT_L(n) asm volatile("s_waitcnt lgkmcnt(" #n ")" ::: "memory")
; #define PG8_BAR __builtin_amdgcn_s_barrier()
; #define PG8_SCHED __builtin_amdgcn_sched_barrier(0)
; template <class Epi, class Sched>
; __device__ __forceinline__ void gemm_phase(PG8_LAS unsigned char* lds, const Gemm g, const Sched& S, const Epi& E) {
;     ...
;             PG8_STAGE(PG8_SB(0, 1), b2 + hstep, voffB);
;             PG8_WAIT_V(6); PG8_BAR; PG8_MMA(1, 1, At, B1); PG8_BAR;
;             PG8_LDB(B0, 1, 0); PG8_SCHED; PG8_LDA(At, 1, 0); PG8_STAGE(PG8_SA(0, 1), a2 + hstep, voffA);
;             PG8_WAIT_L(8); PG8_BAR; PG8_WAIT_L(0); PG8_MMA(0, 0, At, B0); PG8_BAR; PG8_SCHED;
;             PG8_LDB(B1, 1, 1); PG8_STAGE(PG8_SB(1, 0), b3, voffB);
;             PG8_BAR; PG8_WAIT_L(0); PG8_MMA(0, 1, At, B1); PG8_BAR;
;             PG8_LDA(At, 1, 1); PG8_STAGE(PG8_SA(1, 0), a3, voffA);
;             PG8_BAR; PG8_WAIT_L(0); PG8_MMA(1, 0, At, B0); PG8_BAR; PG8_SCHED;
	s_add_u32 s46, s14, 0x40000
	s_addc_u32 s47, s15, 0
	s_add_i32 m0, s20, 0x14000
	s_nop 0
	global_load_lds_dwordx4 v176, s[46:47]
	s_add_i32 m0, s20, 0x16000
	s_nop 0
	global_load_lds_dwordx4 v128, s[46:47]
	s_waitcnt vmcnt(6)
	s_barrier
	v_mfma_f32_16x16x32_bf16 v[44:47], v[194:197], v[158:161], v[44:47]
	v_mfma_f32_16x16x32_bf16 v[40:43], v[202:205], v[158:161], v[40:43]
	v_mfma_f32_16x16x32_bf16 v[28:31], v[194:197], v[166:169], v[28:31]
	v_mfma_f32_16x16x32_bf16 v[24:27], v[202:205], v[166:169], v[24:27]
	v_mfma_f32_16x16x32_bf16 v[12:15], v[194:197], v[178:181], v[12:15]
	v_mfma_f32_16x16x32_bf16 v[8:11], v[202:205], v[178:181], v[8:11]
	v_mfma_f32_16x16x32_bf16 v[4:7], v[194:197], v[186:189], v[4:7]
	v_mfma_f32_16x16x32_bf16 v[0:3], v[202:205], v[186:189], v[0:3]
	v_mfma_f32_16x16x32_bf16 v[44:47], v[198:201], v[162:165], v[44:47]
	v_mfma_f32_16x16x32_bf16 v[40:43], v[206:209], v[162:165], v[40:43]
	v_mfma_f32_16x16x32_bf16 v[28:31], v[198:201], v[170:173], v[28:31]
	v_mfma_f32_16x16x32_bf16 v[24:27], v[206:209], v[170:173], v[24:27]
	v_mfma_f32_16x16x32_bf16 v[12:15], v[198:201], v[182:185], v[12:15]
	v_mfma_f32_16x16x32_bf16 v[8:11], v[206:209], v[182:185], v[8:11]
	v_mfma_f32_16x16x32_bf16 v[4:7], v[198:201], v[190:193], v[4:7]
	v_mfma_f32_16x16x32_bf16 v[0:3], v[206:209], v[190:193], v[0:3]
	v_add_u32_e32 v154, 0x18000, v139
	s_barrier
	ds_read_b128 v[142:145], v154
	ds_read_b128 v[146:149], v154 offset:1024
	ds_read_b128 v[150:153], v154 offset:2048
	ds_read_b128 v[154:157], v154 offset:3072
	s_add_u32 s16, s16, 0x40000
	s_addc_u32 s17, s17, 0
	s_mov_b32 m0, s23
	ds_read_b128 v[158:161], v141 offset:32768
	ds_read_b128 v[162:165], v141 offset:33792
	ds_read_b128 v[166:169], v141 offset:34816
	ds_read_b128 v[170:173], v141 offset:35840
	ds_read_b128 v[178:181], v141 offset:36864
	ds_read_b128 v[182:185], v141 offset:37888
	ds_read_b128 v[186:189], v141 offset:38912
	global_load_lds_dwordx4 v132, s[16:17]
	s_mov_b32 m0, s26
	ds_read_b128 v[190:193], v141 offset:39936
	global_load_lds_dwordx4 v130, s[16:17]
	s_waitcnt lgkmcnt(8)
	s_barrier
	s_waitcnt lgkmcnt(7)
	v_mfma_f32_16x16x32_bf16 v[124:127], v[142:145], v[158:161], v[124:127]
	v_mfma_f32_16x16x32_bf16 v[120:123], v[150:153], v[158:161], v[120:123]
	s_waitcnt lgkmcnt(5)
	v_mfma_f32_16x16x32_bf16 v[116:119], v[142:145], v[166:169], v[116:119]
	v_mfma_f32_16x16x32_bf16 v[112:115], v[150:153], v[166:169], v[112:115]
	s_waitcnt lgkmcnt(3)
	v_mfma_f32_16x16x32_bf16 v[100:103], v[142:145], v[178:181], v[100:103]
	v_mfma_f32_16x16x32_bf16 v[96:99], v[150:153], v[178:181], v[96:99]
	s_waitcnt lgkmcnt(1)
	v_mfma_f32_16x16x32_bf16 v[84:87], v[142:145], v[186:189], v[84:87]
	v_mfma_f32_16x16x32_bf16 v[80:83], v[150:153], v[186:189], v[80:83]
	v_mfma_f32_16x16x32_bf16 v[124:127], v[146:149], v[162:165], v[124:127]
	v_mfma_f32_16x16x32_bf16 v[120:123], v[154:157], v[162:165], v[120:123]
	v_mfma_f32_16x16x32_bf16 v[116:119], v[146:149], v[170:173], v[116:119]
	v_mfma_f32_16x16x32_bf16 v[112:115], v[154:157], v[170:173], v[112:115]
	v_mfma_f32_16x16x32_bf16 v[100:103], v[146:149], v[182:185], v[100:103]
	v_mfma_f32_16x16x32_bf16 v[96:99], v[154:157], v[182:185], v[96:99]
	s_waitcnt lgkmcnt(0)
	v_mfma_f32_16x16x32_bf16 v[84:87], v[146:149], v[190:193], v[84:87]
	v_mfma_f32_16x16x32_bf16 v[80:83], v[154:157], v[190:193], v[80:83]
	s_barrier
	v_add_u32_e32 v206, 0x1c000, v139
	s_add_i32 m0, s20, 0x18000
	ds_read_b128 v[194:197], v206
	ds_read_b128 v[198:201], v206 offset:1024
	ds_read_b128 v[202:205], v206 offset:2048
	global_load_lds_dwordx4 v176, s[98:99]
	s_add_i32 m0, s20, 0x1a000
	ds_read_b128 v[206:209], v206 offset:3072
	global_load_lds_dwordx4 v128, s[98:99]
	s_barrier
	s_waitcnt lgkmcnt(3)
	v_mfma_f32_16x16x32_bf16 v[108:111], v[194:197], v[158:161], v[108:111]
	s_waitcnt lgkmcnt(1)
	v_mfma_f32_16x16x32_bf16 v[104:107], v[202:205], v[158:161], v[104:107]
	v_mfma_f32_16x16x32_bf16 v[92:95], v[194:197], v[166:169], v[92:95]
	v_mfma_f32_16x16x32_bf16 v[88:91], v[202:205], v[166:169], v[88:91]
	v_mfma_f32_16x16x32_bf16 v[76:79], v[194:197], v[178:181], v[76:79]
	v_mfma_f32_16x16x32_bf16 v[72:75], v[202:205], v[178:181], v[72:75]
	v_mfma_f32_16x16x32_bf16 v[68:71], v[194:197], v[186:189], v[68:71]
	v_mfma_f32_16x16x32_bf16 v[64:67], v[202:205], v[186:189], v[64:67]
	v_mfma_f32_16x16x32_bf16 v[108:111], v[198:201], v[162:165], v[108:111]
	s_waitcnt lgkmcnt(0)
	v_mfma_f32_16x16x32_bf16 v[104:107], v[206:209], v[162:165], v[104:107]
	v_mfma_f32_16x16x32_bf16 v[92:95], v[198:201], v[170:173], v[92:95]
	v_mfma_f32_16x16x32_bf16 v[88:91], v[206:209], v[170:173], v[88:91]
	v_mfma_f32_16x16x32_bf16 v[76:79], v[198:201], v[182:185], v[76:79]
	v_mfma_f32_16x16x32_bf16 v[72:75], v[206:209], v[182:185], v[72:75]
	v_mfma_f32_16x16x32_bf16 v[68:71], v[198:201], v[190:193], v[68:71]
	v_mfma_f32_16x16x32_bf16 v[64:67], v[206:209], v[190:193], v[64:67]
	s_mov_b32 m0, s28
	s_barrier
	ds_read_b128 v[158:161], v141 offset:49152
	ds_read_b128 v[162:165], v141 offset:50176
	ds_read_b128 v[166:169], v141 offset:51200
	ds_read_b128 v[170:173], v141 offset:52224
	ds_read_b128 v[178:181], v141 offset:53248
	ds_read_b128 v[182:185], v141 offset:54272
	ds_read_b128 v[186:189], v141 offset:55296
	global_load_lds_dwordx4 v132, s[100:101]
	s_mov_b32 m0, s29
	ds_read_b128 v[190:193], v141 offset:56320
	global_load_lds_dwordx4 v130, s[100:101]
	s_barrier
; #define PG8_STAGE(bufoff, gbase, voff) do { _Pragma("unroll") for (int _i = 0; _i < 2; ++_i) \
;         __builtin_amdgcn_global_load_lds((const unsigned*)((const char*)(gbase) + (voff)[_i]), (PG8_LAS unsigned*)(lds + (bufoff) + ldsw + _i * 8192), 16, 0, 0); } while (0)
; #define PG8_MMA(ai, bj, At, Bt) do { __builtin_amdgcn_s_setprio(1); _Pragma("unroll") for (int m = 0; m < 4; ++m) _Pragma("unroll") for (int n = 0; n < 2; ++n) _Pragma("unroll") for (int k = 0; k < 2; ++k) \
;         acc[ai][bj][m][n] = __builtin_amdgcn_mfma_f32_16x16x32_bf16(Bt[n][k], At[m][k], acc[ai][bj][m][n], 0, 0, 0); __builtin_amdgcn_s_setprio(0); } while (0)
; #define PG8_WAIT_V(n) asm volatile("s_waitcnt vmcnt(" #n ")" ::: "memory")
; #define PG8_WAIT_L(n) asm volatile("s_waitcnt lgkmcnt(" #n ")" ::: "memory")
; #define PG8_BAR __builtin_amdgcn_s_barrier()
; #define PG8_SCHED __builtin_amdgcn_sched_barrier(0)
; template <class Epi, class Sched>
; __device__ __forceinline__ void gemm_phase(PG8_LAS unsigned char* lds, const Gemm g, const Sched& S, const Epi& E) {
;     ...
;             PG8_BAR; PG8_WAIT_L(0); PG8_MMA(1, 0, At, B0); PG8_BAR; PG8_SCHED;
;             PG8_STAGE(PG8_SB(1, 1), b3 + hstep, voffB);
;             PG8_WAIT_V(6); PG8_BAR; PG8_MMA(1, 1, At, B1); PG8_BAR;
;         }
	s_waitcnt lgkmcnt(7)
	v_mfma_f32_16x16x32_bf16 v[60:63], v[142:145], v[158:161], v[60:63]
	v_mfma_f32_16x16x32_bf16 v[56:59], v[150:153], v[158:161], v[56:59]
	s_waitcnt lgkmcnt(5)
	v_mfma_f32_16x16x32_bf16 v[52:55], v[142:145], v[166:169], v[52:55]
	v_mfma_f32_16x16x32_bf16 v[48:51], v[150:153], v[166:169], v[48:51]
	s_waitcnt lgkmcnt(3)
	v_mfma_f32_16x16x32_bf16 v[36:39], v[142:145], v[178:181], v[36:39]
	v_mfma_f32_16x16x32_bf16 v[32:35], v[150:153], v[178:181], v[32:35]
	s_waitcnt lgkmcnt(1)
	v_mfma_f32_16x16x32_bf16 v[20:23], v[142:145], v[186:189], v[20:23]
	v_mfma_f32_16x16x32_bf16 v[16:19], v[150:153], v[186:189], v[16:19]
	v_mfma_f32_16x16x32_bf16 v[60:63], v[146:149], v[162:165], v[60:63]
	v_mfma_f32_16x16x32_bf16 v[56:59], v[154:157], v[162:165], v[56:59]
	v_mfma_f32_16x16x32_bf16 v[52:55], v[146:149], v[170:173], v[52:55]
	v_mfma_f32_16x16x32_bf16 v[48:51], v[154:157], v[170:173], v[48:51]
	v_mfma_f32_16x16x32_bf16 v[36:39], v[146:149], v[182:185], v[36:39]
	v_mfma_f32_16x16x32_bf16 v[32:35], v[154:157], v[182:185], v[32:35]
	s_waitcnt lgkmcnt(0)
	v_mfma_f32_16x16x32_bf16 v[20:23], v[146:149], v[190:193], v[20:23]
	v_mfma_f32_16x16x32_bf16 v[16:19], v[154:157], v[190:193], v[16:19]
	s_barrier
	s_add_u32 s14, s14, 0x40080
	s_addc_u32 s15, s15, 0
	s_add_i32 m0, s20, 0x1c000
	s_nop 0
	global_load_lds_dwordx4 v176, s[14:15]
	s_add_i32 m0, s20, 0x1e000
	s_nop 0
	global_load_lds_dwordx4 v128, s[14:15]
	s_waitcnt vmcnt(6)
	s_barrier
	v_mfma_f32_16x16x32_bf16 v[44:47], v[194:197], v[158:161], v[44:47]
	v_mfma_f32_16x16x32_bf16 v[40:43], v[202:205], v[158:161], v[40:43]
	v_mfma_f32_16x16x32_bf16 v[28:31], v[194:197], v[166:169], v[28:31]
	v_mfma_f32_16x16x32_bf16 v[24:27], v[202:205], v[166:169], v[24:27]
	v_mfma_f32_16x16x32_bf16 v[12:15], v[194:197], v[178:181], v[12:15]
	v_mfma_f32_16x16x32_bf16 v[8:11], v[202:205], v[178:181], v[8:11]
	v_mfma_f32_16x16x32_bf16 v[4:7], v[194:197], v[186:189], v[4:7]
	v_mfma_f32_16x16x32_bf16 v[0:3], v[202:205], v[186:189], v[0:3]
	v_mfma_f32_16x16x32_bf16 v[44:47], v[198:201], v[162:165], v[44:47]
	v_mfma_f32_16x16x32_bf16 v[40:43], v[206:209], v[162:165], v[40:43]
	v_mfma_f32_16x16x32_bf16 v[28:31], v[198:201], v[170:173], v[28:31]
	v_mfma_f32_16x16x32_bf16 v[24:27], v[206:209], v[170:173], v[24:27]
	v_mfma_f32_16x16x32_bf16 v[12:15], v[198:201], v[182:185], v[12:15]
	v_mfma_f32_16x16x32_bf16 v[8:11], v[206:209], v[182:185], v[8:11]
	v_mfma_f32_16x16x32_bf16 v[4:7], v[198:201], v[190:193], v[4:7]
	v_mfma_f32_16x16x32_bf16 v[0:3], v[206:209], v[190:193], v[0:3]
	s_add_i32 s45, s45, 2
	s_add_u32 s12, s12, 0x100
	s_addc_u32 s13, s13, 0
	s_add_u32 s43, s43, 0x100
	s_addc_u32 s44, s44, 0
	s_cmp_gt_u32 s45, 13
	s_barrier
	s_cbranch_scc0 .LBB0_137
; __device__ __forceinline__ unsigned cvtpk(float lo, float hi) { const f32x2 v = (f32x2){lo, hi}; const bf16v2 b = __builtin_convertvector(v, bf16v2); return __builtin_bit_cast(unsigned, b); }
;     __device__ __forceinline__ void operator()(const f32x4 (&acc)[2][2][4][2], const pg8::Unit& u, int wr, int wc, int fr, int fq) const {
;         const int row0 = u.pm * 256 + wr * 64 + fr, col0 = u.pn * 256 + wc * 32 + 8 * fq;
; #pragma unroll
;         for (int ai = 0; ai < 2; ++ai)
; #pragma unroll
;             for (int m = 0; m < 4; ++m) { bf16_t* rowp = O + (size_t)(row0 + ai * 128 + m * 16) * ldc + col0;
; #pragma unroll
;                 for (int bj = 0; bj < 2; ++bj) { const f32x4 v0 = acc[ai][bj][m][0], v1 = acc[ai][bj][m][1];
;                     u32x4 w; w.x = cvtpk(v0[0], v0[1]); w.y = cvtpk(v0[2], v0[3]); w.z = cvtpk(v1[0], v1[1]); w.w = cvtpk(v1[2], v1[3]);
;                     *(u32x4*)(rowp + bj * 128) = w; } }
;     }
	v_lshl_add_u32 v142, s0, 8, v138
	v_lshl_or_b32 v144, s34, 8, v140
	v_ashrrev_i32_e32 v143, 31, v142
	v_readlane_b32 s12, v253, 18
	v_ashrrev_i32_e32 v145, 31, v144
	v_lshlrev_b64 v[146:147], 11, v[142:143]
	v_readlane_b32 s13, v253, 19
	v_cvt_pk_bf16_f32 v108, v108, v109
	v_cvt_pk_bf16_f32 v109, v110, v111
	v_cvt_pk_bf16_f32 v110, v104, v105
	v_or_b32_e32 v104, 16, v142
	v_cvt_pk_bf16_f32 v92, v92, v93
	v_cvt_pk_bf16_f32 v93, v94, v95
	v_cvt_pk_bf16_f32 v94, v88, v89
	v_or_b32_e32 v88, 32, v142
	v_cvt_pk_bf16_f32 v76, v76, v77
	v_cvt_pk_bf16_f32 v77, v78, v79
	v_cvt_pk_bf16_f32 v78, v72, v73
	v_or_b32_e32 v72, 48, v142
	v_lshl_add_u64 v[146:147], s[12:13], 0, v[146:147]
	v_lshlrev_b64 v[144:145], 1, v[144:145]
	v_ashrrev_i32_e32 v105, 31, v104
	v_ashrrev_i32_e32 v89, 31, v88
	v_ashrrev_i32_e32 v73, 31, v72
	v_lshl_add_u64 v[146:147], v[146:147], 0, v[144:145]
	v_lshlrev_b64 v[104:105], 11, v[104:105]
	v_lshlrev_b64 v[88:89], 11, v[88:89]
	v_lshlrev_b64 v[72:73], 11, v[72:73]
	v_lshl_add_u64 v[104:105], s[12:13], 0, v[104:105]
	v_lshl_add_u64 v[88:89], s[12:13], 0, v[88:89]
	v_lshl_add_u64 v[72:73], s[12:13], 0, v[72:73]
	s_mov_b64 s[12:13], 0x40000
	v_cvt_pk_bf16_f32 v60, v60, v61
	v_cvt_pk_bf16_f32 v61, v62, v63
	v_cvt_pk_bf16_f32 v62, v56, v57
	v_add_co_u32_e32 v56, vcc, s2, v146
	v_cvt_pk_bf16_f32 v68, v68, v69
	v_cvt_pk_bf16_f32 v69, v70, v71
	v_cvt_pk_bf16_f32 v70, v64, v65
	v_lshl_add_u64 v[64:65], v[146:147], 0, s[12:13]
	v_addc_co_u32_e32 v57, vcc, 0, v147, vcc
	v_cvt_pk_bf16_f32 v44, v44, v45
	v_cvt_pk_bf16_f32 v45, v46, v47
	v_cvt_pk_bf16_f32 v46, v40, v41
	v_cvt_pk_bf16_f32 v47, v42, v43
	s_mov_b32 s0, 0x48000
	global_store_dwordx4 v[64:65], v[44:47], off offset:256 sc1
	s_mov_b64 s[12:13], 0x48000
	v_cvt_pk_bf16_f32 v28, v28, v29
	v_add_co_u32_e32 v46, vcc, s0, v146
	v_lshl_add_u64 v[44:45], v[146:147], 0, s[12:13]
	s_nop 0
	v_addc_co_u32_e32 v47, vcc, 0, v147, vcc
	v_cvt_pk_bf16_f32 v29, v30, v31
	v_cvt_pk_bf16_f32 v30, v24, v25
	v_cvt_pk_bf16_f32 v31, v26, v27
	s_mov_b32 s0, 0x50000
	global_store_dwordx4 v[44:45], v[28:31], off offset:256 sc1
	s_mov_b64 s[12:13], 0x50000
	v_cvt_pk_bf16_f32 v111, v106, v107
	v_add_co_u32_e32 v30, vcc, s0, v146
	v_lshl_add_u64 v[28:29], v[146:147], 0, s[12:13]
	s_nop 0
	v_addc_co_u32_e32 v31, vcc, 0, v147, vcc
	v_cvt_pk_bf16_f32 v12, v12, v13
	v_cvt_pk_bf16_f32 v13, v14, v15
	v_cvt_pk_bf16_f32 v14, v8, v9
	v_cvt_pk_bf16_f32 v15, v10, v11
	s_mov_b32 s0, 0x58000
	global_store_dwordx4 v[146:147], v[108:111], off offset:256 sc1
	v_cvt_pk_bf16_f32 v95, v90, v91
	global_store_dwordx4 v[28:29], v[12:15], off offset:256 sc1
	v_lshl_add_u64 v[108:109], v[104:105], 0, v[144:145]
	global_store_dwordx4 v[108:109], v[92:95], off offset:256 sc1
	v_add_co_u32_e32 v14, vcc, s0, v146
	s_nop 0
	v_lshl_add_u64 v[92:93], v[88:89], 0, v[144:145]
	v_cvt_pk_bf16_f32 v79, v74, v75
	s_mov_b64 s[12:13], 0x58000
	v_addc_co_u32_e32 v15, vcc, 0, v147, vcc
	v_cvt_pk_bf16_f32 v124, v124, v125
	v_cvt_pk_bf16_f32 v125, v126, v127
	v_cvt_pk_bf16_f32 v126, v120, v121
	v_cvt_pk_bf16_f32 v127, v122, v123
	v_cvt_pk_bf16_f32 v104, v116, v117
	v_cvt_pk_bf16_f32 v105, v118, v119
	v_cvt_pk_bf16_f32 v106, v112, v113
	v_cvt_pk_bf16_f32 v107, v114, v115
	v_cvt_pk_bf16_f32 v88, v100, v101
	v_cvt_pk_bf16_f32 v89, v102, v103
	v_cvt_pk_bf16_f32 v90, v96, v97
	v_cvt_pk_bf16_f32 v91, v98, v99
	global_store_dwordx4 v[92:93], v[76:79], off offset:256 sc1
	v_cvt_pk_bf16_f32 v74, v80, v81
	v_cvt_pk_bf16_f32 v75, v82, v83
	v_lshl_add_u64 v[76:77], v[72:73], 0, v[144:145]
	v_cvt_pk_bf16_f32 v72, v84, v85
	v_cvt_pk_bf16_f32 v73, v86, v87
	v_cvt_pk_bf16_f32 v71, v66, v67
	v_cvt_pk_bf16_f32 v63, v58, v59
	v_cvt_pk_bf16_f32 v40, v52, v53
	v_cvt_pk_bf16_f32 v41, v54, v55
	v_cvt_pk_bf16_f32 v42, v48, v49
	v_cvt_pk_bf16_f32 v43, v50, v51
	v_cvt_pk_bf16_f32 v24, v36, v37
	v_cvt_pk_bf16_f32 v25, v38, v39
	v_cvt_pk_bf16_f32 v26, v32, v33
	v_cvt_pk_bf16_f32 v27, v34, v35
	v_lshl_add_u64 v[12:13], v[146:147], 0, s[12:13]
	v_cvt_pk_bf16_f32 v8, v20, v21
	v_cvt_pk_bf16_f32 v9, v22, v23
	v_cvt_pk_bf16_f32 v10, v16, v17
	v_cvt_pk_bf16_f32 v11, v18, v19
	v_cvt_pk_bf16_f32 v4, v4, v5
	v_cvt_pk_bf16_f32 v5, v6, v7
	v_cvt_pk_bf16_f32 v6, v0, v1
	v_cvt_pk_bf16_f32 v7, v2, v3
	s_and_b64 vcc, exec, s[38:39]
	s_mov_b32 s34, s4
	s_mov_b32 s0, s6
	s_mov_b64 s[14:15], s[10:11]
	s_mov_b64 s[12:13], s[8:9]
	global_store_dwordx4 v[146:147], v[124:127], off sc1
	global_store_dwordx4 v[108:109], v[104:107], off sc1
	global_store_dwordx4 v[92:93], v[88:91], off sc1
	global_store_dwordx4 v[76:77], v[72:75], off sc1
	global_store_dwordx4 v[76:77], v[68:71], off offset:256 sc1
	global_store_dwordx4 v[56:57], v[60:63], off sc1
	global_store_dwordx4 v[46:47], v[40:43], off sc1
	global_store_dwordx4 v[30:31], v[24:27], off sc1
	global_store_dwordx4 v[14:15], v[8:11], off sc1
	global_store_dwordx4 v[12:13], v[4:7], off offset:256 sc1
	s_cbranch_vccz .LBB0_134
	s_waitcnt vmcnt(0)
	v_readlane_b32 s22, v255, 14
	s_cmpk_gt_u32 s19, 0xff
	v_readlane_b32 s23, v255, 15
	s_mov_b64 s[28:29], s[54:55]
	s_cbranch_scc1 .LBB0_141
	s_barrier

; #define PG8_STAGE(bufoff, gbase, voff) do { _Pragma("unroll") for (int _i = 0; _i < 2; ++_i) \
;         __builtin_amdgcn_global_load_lds((const unsigned*)((const char*)(gbase) + (voff)[_i]), (PG8_LAS unsigned*)(lds + (bufoff) + ldsw + _i * 8192), 16, 0, 0); } while (0)
; #define PG8_LDA(dst, b, h) do { _Pragma("unroll") for (int m = 0; m < 4; ++m) _Pragma("unroll") for (int k = 0; k < 2; ++k) dst[m][k] = *(const PG8_LAS bf16x8*)(lds + PG8_SA(b, h) + aoff + m * 2048 + k * 1024); } while (0)
; #define PG8_LDB(dst, b, h) do { _Pragma("unroll") for (int n = 0; n < 2; ++n) _Pragma("unroll") for (int k = 0; k < 2; ++k) dst[n][k] = *(const PG8_LAS bf16x8*)(lds + PG8_SB(b, h) + boff + n * 2048 + k * 1024); } while (0)
; #define PG8_MMA(ai, bj, At, Bt) do { __builtin_amdgcn_s_setprio(1); _Pragma("unroll") for (int m = 0; m < 4; ++m) _Pragma("unroll") for (int n = 0; n < 2; ++n) _Pragma("unroll") for (int k = 0; k < 2; ++k) \
;         acc[ai][bj][m][n] = __builtin_amdgcn_mfma_f32_16x16x32_bf16(Bt[n][k], At[m][k], acc[ai][bj][m][n], 0, 0, 0); __builtin_amdgcn_s_setprio(0); } while (0)
; #define PG8_WAIT_V(n) asm volatile("s_waitcnt vmcnt(" #n ")" ::: "memory")
; #define PG8_WAIT_L(n) asm volatile("s_waitcnt lgkmcnt(" #n ")" ::: "memory")
; #define PG8_BAR __builtin_amdgcn_s_barrier()
; #define PG8_SCHED __builtin_amdgcn_sched_barrier(0)
; template <class Epi, class Sched>
; __device__ __forceinline__ void gemm_phase(PG8_LAS unsigned char* lds, const Gemm g, const Sched& S, const Epi& E) {
;     ...
;             PG8_LDB(B0, 0, 0); PG8_SCHED; PG8_LDA(At, 0, 0); PG8_STAGE(PG8_SA(1, 1), a1 + hstep, voffA);
;             PG8_WAIT_L(8); PG8_BAR; PG8_WAIT_L(0); PG8_MMA(0, 0, At, B0); PG8_BAR; PG8_SCHED;
;             PG8_LDB(B1, 0, 1); PG8_STAGE(PG8_SB(0, 0), b2, voffB);
;             PG8_BAR; PG8_WAIT_L(0); PG8_MMA(0, 1, At, B1); PG8_BAR;
;             PG8_LDA(At, 0, 1); PG8_STAGE(PG8_SA(0, 0), a2, voffA);
;             PG8_BAR; PG8_WAIT_L(0); PG8_MMA(1, 0, At, B0); PG8_BAR; PG8_SCHED;
;             PG8_STAGE(PG8_SB(0, 1), b2 + hstep, voffB);
;             PG8_WAIT_V(6); PG8_BAR; PG8_MMA(1, 1, At, B1); PG8_BAR;
.LBB0_358:
	s_add_u32 s14, s12, 0xfffc0080
	s_addc_u32 s15, s13, -1
	v_add_u32_e32 v154, 0x10000, v139
	ds_read_b128 v[142:145], v154
	ds_read_b128 v[146:149], v154 offset:1024
	ds_read_b128 v[150:153], v154 offset:2048
	ds_read_b128 v[154:157], v154 offset:3072
	s_cmp_eq_u32 s45, 12
	s_cselect_b32 s17, s7, s15
	s_cselect_b32 s16, s40, s14
	s_cselect_b32 s15, s5, s44
	s_cselect_b32 s14, s41, s43
	s_add_i32 m0, s1, 0xc000
	ds_read_b128 v[158:161], v141
	ds_read_b128 v[162:165], v141 offset:1024
	ds_read_b128 v[166:169], v141 offset:2048
	ds_read_b128 v[170:173], v141 offset:3072
	ds_read_b128 v[182:185], v141 offset:4096
	ds_read_b128 v[190:193], v141 offset:5120
	ds_read_b128 v[194:197], v141 offset:6144
	global_load_lds_dwordx4 v134, s[12:13]
	s_add_i32 m0, s1, 0xe000
	ds_read_b128 v[198:201], v141 offset:7168
	global_load_lds_dwordx4 v136, s[12:13]
	s_waitcnt lgkmcnt(8)
	s_barrier
	s_waitcnt lgkmcnt(7)
	v_mfma_f32_16x16x32_bf16 v[124:127], v[142:145], v[158:161], v[124:127]
	v_mfma_f32_16x16x32_bf16 v[120:123], v[150:153], v[158:161], v[120:123]
	s_waitcnt lgkmcnt(5)
	v_mfma_f32_16x16x32_bf16 v[116:119], v[142:145], v[166:169], v[116:119]
	v_mfma_f32_16x16x32_bf16 v[112:115], v[150:153], v[166:169], v[112:115]
	s_waitcnt lgkmcnt(3)
	v_mfma_f32_16x16x32_bf16 v[100:103], v[142:145], v[182:185], v[100:103]
	v_mfma_f32_16x16x32_bf16 v[96:99], v[150:153], v[182:185], v[96:99]
	s_waitcnt lgkmcnt(1)
	v_mfma_f32_16x16x32_bf16 v[84:87], v[142:145], v[194:197], v[84:87]
	v_mfma_f32_16x16x32_bf16 v[80:83], v[150:153], v[194:197], v[80:83]
	v_mfma_f32_16x16x32_bf16 v[124:127], v[146:149], v[162:165], v[124:127]
	v_mfma_f32_16x16x32_bf16 v[120:123], v[154:157], v[162:165], v[120:123]
	v_mfma_f32_16x16x32_bf16 v[116:119], v[146:149], v[170:173], v[116:119]
	v_mfma_f32_16x16x32_bf16 v[112:115], v[154:157], v[170:173], v[112:115]
	v_mfma_f32_16x16x32_bf16 v[100:103], v[146:149], v[190:193], v[100:103]
	v_mfma_f32_16x16x32_bf16 v[96:99], v[154:157], v[190:193], v[96:99]
	s_waitcnt lgkmcnt(0)
	v_mfma_f32_16x16x32_bf16 v[84:87], v[146:149], v[198:201], v[84:87]
	v_mfma_f32_16x16x32_bf16 v[80:83], v[154:157], v[198:201], v[80:83]
	s_barrier
	s_add_i32 s48, 0, 0x14000
	v_add_u32_e32 v174, 0x14000, v139
	ds_read_b128 v[202:205], v174
	ds_read_b128 v[206:209], v174 offset:1024
	s_add_u32 s98, s14, 0x80
	s_addc_u32 s99, s15, 0
	s_add_i32 m0, s20, 0x10000
	ds_read_b128 v[210:213], v174 offset:2048
	global_load_lds_dwordx4 v176, s[14:15]
	s_add_i32 m0, s20, 0x12000
	ds_read_b128 v[214:217], v174 offset:3072
	global_load_lds_dwordx4 v128, s[14:15]
	s_barrier
	s_waitcnt lgkmcnt(3)
	v_mfma_f32_16x16x32_bf16 v[108:111], v[202:205], v[158:161], v[108:111]
	s_waitcnt lgkmcnt(1)
	v_mfma_f32_16x16x32_bf16 v[104:107], v[210:213], v[158:161], v[104:107]
	v_mfma_f32_16x16x32_bf16 v[92:95], v[202:205], v[166:169], v[92:95]
	v_mfma_f32_16x16x32_bf16 v[88:91], v[210:213], v[166:169], v[88:91]
	v_mfma_f32_16x16x32_bf16 v[76:79], v[202:205], v[182:185], v[76:79]
	v_mfma_f32_16x16x32_bf16 v[72:75], v[210:213], v[182:185], v[72:75]
	v_mfma_f32_16x16x32_bf16 v[68:71], v[202:205], v[194:197], v[68:71]
	v_mfma_f32_16x16x32_bf16 v[64:67], v[210:213], v[194:197], v[64:67]
	v_mfma_f32_16x16x32_bf16 v[108:111], v[206:209], v[162:165], v[108:111]
	s_waitcnt lgkmcnt(0)
	v_mfma_f32_16x16x32_bf16 v[104:107], v[214:217], v[162:165], v[104:107]
	v_mfma_f32_16x16x32_bf16 v[92:95], v[206:209], v[170:173], v[92:95]
	v_mfma_f32_16x16x32_bf16 v[88:91], v[214:217], v[170:173], v[88:91]
	v_mfma_f32_16x16x32_bf16 v[76:79], v[206:209], v[190:193], v[76:79]
	v_mfma_f32_16x16x32_bf16 v[72:75], v[214:217], v[190:193], v[72:75]
	v_mfma_f32_16x16x32_bf16 v[68:71], v[206:209], v[198:201], v[68:71]
	v_mfma_f32_16x16x32_bf16 v[64:67], v[214:217], v[198:201], v[64:67]
	s_mov_b32 m0, s1
	s_add_u32 s100, s16, 0x80
	s_addc_u32 s101, s17, 0
	s_barrier
	ds_read_b128 v[158:161], v141 offset:16384
	ds_read_b128 v[162:165], v141 offset:17408
	ds_read_b128 v[166:169], v141 offset:18432
	ds_read_b128 v[170:173], v141 offset:19456
	ds_read_b128 v[182:185], v141 offset:20480
	ds_read_b128 v[190:193], v141 offset:21504
	ds_read_b128 v[194:197], v141 offset:22528
	global_load_lds_dwordx4 v132, s[16:17]
	s_mov_b32 m0, s22
	ds_read_b128 v[198:201], v141 offset:23552
	global_load_lds_dwordx4 v130, s[16:17]
	s_barrier
	s_waitcnt lgkmcnt(7)
	v_mfma_f32_16x16x32_bf16 v[60:63], v[142:145], v[158:161], v[60:63]
	v_mfma_f32_16x16x32_bf16 v[56:59], v[150:153], v[158:161], v[56:59]
	s_waitcnt lgkmcnt(5)
	v_mfma_f32_16x16x32_bf16 v[52:55], v[142:145], v[166:169], v[52:55]
	v_mfma_f32_16x16x32_bf16 v[48:51], v[150:153], v[166:169], v[48:51]
	s_waitcnt lgkmcnt(3)
	v_mfma_f32_16x16x32_bf16 v[36:39], v[142:145], v[182:185], v[36:39]
	v_mfma_f32_16x16x32_bf16 v[32:35], v[150:153], v[182:185], v[32:35]
	s_waitcnt lgkmcnt(1)
	v_mfma_f32_16x16x32_bf16 v[20:23], v[142:145], v[194:197], v[20:23]
	v_mfma_f32_16x16x32_bf16 v[16:19], v[150:153], v[194:197], v[16:19]
	v_mfma_f32_16x16x32_bf16 v[60:63], v[146:149], v[162:165], v[60:63]
	v_mfma_f32_16x16x32_bf16 v[56:59], v[154:157], v[162:165], v[56:59]
	v_mfma_f32_16x16x32_bf16 v[52:55], v[146:149], v[170:173], v[52:55]
	v_mfma_f32_16x16x32_bf16 v[48:51], v[154:157], v[170:173], v[48:51]
	v_mfma_f32_16x16x32_bf16 v[36:39], v[146:149], v[190:193], v[36:39]
	v_mfma_f32_16x16x32_bf16 v[32:35], v[154:157], v[190:193], v[32:35]
	s_waitcnt lgkmcnt(0)
	v_mfma_f32_16x16x32_bf16 v[20:23], v[146:149], v[198:201], v[20:23]
	v_mfma_f32_16x16x32_bf16 v[16:19], v[154:157], v[198:201], v[16:19]
	s_barrier
; #define PG8_STAGE(bufoff, gbase, voff) do { _Pragma("unroll") for (int _i = 0; _i < 2; ++_i) \
;         __builtin_amdgcn_global_load_lds((const unsigned*)((const char*)(gbase) + (voff)[_i]), (PG8_LAS unsigned*)(lds + (bufoff) + ldsw + _i * 8192), 16, 0, 0); } while (0)
; #define PG8_LDA(dst, b, h) do { _Pragma("unroll") for (int m = 0; m < 4; ++m) _Pragma("unroll") for (int k = 0; k < 2; ++k) dst[m][k] = *(const PG8_LAS bf16x8*)(lds + PG8_SA(b, h) + aoff + m * 2048 + k * 1024); } while (0)
; #define PG8_LDB(dst, b, h) do { _Pragma("unroll") for (int n = 0; n < 2; ++n) _Pragma("unroll") for (int k = 0; k < 2; ++k) dst[n][k] = *(const PG8_LAS bf16x8*)(lds + PG8_SB(b, h) + boff + n * 2048 + k * 1024); } while (0)
; #define PG8_MMA(ai, bj, At, Bt) do { __builtin_amdgcn_s_setprio(1); _Pragma("unroll") for (int m = 0; m < 4; ++m) _Pragma("unroll") for (int n = 0; n < 2; ++n) _Pragma("unroll") for (int k = 0; k < 2; ++k) \
;         acc[ai][bj][m][n] = __builtin_amdgcn_mfma_f32_16x16x32_bf16(Bt[n][k], At[m][k], acc[ai][bj][m][n], 0, 0, 0); __builtin_amdgcn_s_setprio(0); } while (0)
; #define PG8_WAIT_V(n) asm volatile("s_waitcnt vmcnt(" #n ")" ::: "memory")
; #define PG8_WAIT_L(n) asm volatile("s_waitcnt lgkmcnt(" #n ")" ::: "memory")
; #define PG8_BAR __builtin_amdgcn_s_barrier()
; #define PG8_SCHED __builtin_amdgcn_sched_barrier(0)
; template <class Epi, class Sched>
; __device__ __forceinline__ void gemm_phase(PG8_LAS unsigned char* lds, const Gemm g, const Sched& S, const Epi& E) {
;     ...
;             PG8_STAGE(PG8_SB(0, 1), b2 + hstep, voffB);
;             PG8_WAIT_V(6); PG8_BAR; PG8_MMA(1, 1, At, B1); PG8_BAR;
;             PG8_LDB(B0, 1, 0); PG8_SCHED; PG8_LDA(At, 1, 0); PG8_STAGE(PG8_SA(0, 1), a2 + hstep, voffA);
;             PG8_WAIT_L(8); PG8_BAR; PG8_WAIT_L(0); PG8_MMA(0, 0, At, B0); PG8_BAR; PG8_SCHED;
;             PG8_LDB(B1, 1, 1); PG8_STAGE(PG8_SB(1, 0), b3, voffB);
;             PG8_BAR; PG8_WAIT_L(0); PG8_MMA(0, 1, At, B1); PG8_BAR;
;             PG8_LDA(At, 1, 1); PG8_STAGE(PG8_SA(1, 0), a3, voffA);
;             PG8_BAR; PG8_WAIT_L(0); PG8_MMA(1, 0, At, B0); PG8_BAR; PG8_SCHED;
	s_add_u32 s46, s14, 0x40000
	s_addc_u32 s47, s15, 0
	s_add_i32 m0, s20, 0x14000
	s_nop 0
	global_load_lds_dwordx4 v176, s[46:47]
	s_add_i32 m0, s20, 0x16000
	s_nop 0
	global_load_lds_dwordx4 v128, s[46:47]
	s_waitcnt vmcnt(6)
	s_barrier
	v_mfma_f32_16x16x32_bf16 v[44:47], v[202:205], v[158:161], v[44:47]
	v_mfma_f32_16x16x32_bf16 v[40:43], v[210:213], v[158:161], v[40:43]
	v_mfma_f32_16x16x32_bf16 v[28:31], v[202:205], v[166:169], v[28:31]
	v_mfma_f32_16x16x32_bf16 v[24:27], v[210:213], v[166:169], v[24:27]
	v_mfma_f32_16x16x32_bf16 v[12:15], v[202:205], v[182:185], v[12:15]
	v_mfma_f32_16x16x32_bf16 v[8:11], v[210:213], v[182:185], v[8:11]
	v_mfma_f32_16x16x32_bf16 v[4:7], v[202:205], v[194:197], v[4:7]
	v_mfma_f32_16x16x32_bf16 v[0:3], v[210:213], v[194:197], v[0:3]
	v_mfma_f32_16x16x32_bf16 v[44:47], v[206:209], v[162:165], v[44:47]
	v_mfma_f32_16x16x32_bf16 v[40:43], v[214:217], v[162:165], v[40:43]
	v_mfma_f32_16x16x32_bf16 v[28:31], v[206:209], v[170:173], v[28:31]
	v_mfma_f32_16x16x32_bf16 v[24:27], v[214:217], v[170:173], v[24:27]
	v_mfma_f32_16x16x32_bf16 v[12:15], v[206:209], v[190:193], v[12:15]
	v_mfma_f32_16x16x32_bf16 v[8:11], v[214:217], v[190:193], v[8:11]
	v_mfma_f32_16x16x32_bf16 v[4:7], v[206:209], v[198:201], v[4:7]
	v_mfma_f32_16x16x32_bf16 v[0:3], v[214:217], v[198:201], v[0:3]
	v_add_u32_e32 v154, 0x18000, v139
	s_barrier
	ds_read_b128 v[142:145], v154
	ds_read_b128 v[146:149], v154 offset:1024
	ds_read_b128 v[150:153], v154 offset:2048
	ds_read_b128 v[154:157], v154 offset:3072
	s_add_u32 s16, s16, 0x40000
	s_addc_u32 s17, s17, 0
	s_mov_b32 m0, s23
	ds_read_b128 v[158:161], v141 offset:32768
	ds_read_b128 v[162:165], v141 offset:33792
	ds_read_b128 v[166:169], v141 offset:34816
	ds_read_b128 v[170:173], v141 offset:35840
	ds_read_b128 v[182:185], v141 offset:36864
	ds_read_b128 v[190:193], v141 offset:37888
	ds_read_b128 v[194:197], v141 offset:38912
	global_load_lds_dwordx4 v132, s[16:17]
	s_mov_b32 m0, s26
	ds_read_b128 v[198:201], v141 offset:39936
	global_load_lds_dwordx4 v130, s[16:17]
	s_waitcnt lgkmcnt(8)
	s_barrier
	s_waitcnt lgkmcnt(7)
	v_mfma_f32_16x16x32_bf16 v[124:127], v[142:145], v[158:161], v[124:127]
	v_mfma_f32_16x16x32_bf16 v[120:123], v[150:153], v[158:161], v[120:123]
	s_waitcnt lgkmcnt(5)
	v_mfma_f32_16x16x32_bf16 v[116:119], v[142:145], v[166:169], v[116:119]
	v_mfma_f32_16x16x32_bf16 v[112:115], v[150:153], v[166:169], v[112:115]
	s_waitcnt lgkmcnt(3)
	v_mfma_f32_16x16x32_bf16 v[100:103], v[142:145], v[182:185], v[100:103]
	v_mfma_f32_16x16x32_bf16 v[96:99], v[150:153], v[182:185], v[96:99]
	s_waitcnt lgkmcnt(1)
	v_mfma_f32_16x16x32_bf16 v[84:87], v[142:145], v[194:197], v[84:87]
	v_mfma_f32_16x16x32_bf16 v[80:83], v[150:153], v[194:197], v[80:83]
	v_mfma_f32_16x16x32_bf16 v[124:127], v[146:149], v[162:165], v[124:127]
	v_mfma_f32_16x16x32_bf16 v[120:123], v[154:157], v[162:165], v[120:123]
	v_mfma_f32_16x16x32_bf16 v[116:119], v[146:149], v[170:173], v[116:119]
	v_mfma_f32_16x16x32_bf16 v[112:115], v[154:157], v[170:173], v[112:115]
	v_mfma_f32_16x16x32_bf16 v[100:103], v[146:149], v[190:193], v[100:103]
	v_mfma_f32_16x16x32_bf16 v[96:99], v[154:157], v[190:193], v[96:99]
	s_waitcnt lgkmcnt(0)
	v_mfma_f32_16x16x32_bf16 v[84:87], v[146:149], v[198:201], v[84:87]
	v_mfma_f32_16x16x32_bf16 v[80:83], v[154:157], v[198:201], v[80:83]
	s_barrier
	v_add_u32_e32 v188, 0x1c000, v139
	s_add_i32 m0, s20, 0x18000
	ds_read_b128 v[202:205], v188
	ds_read_b128 v[206:209], v188 offset:1024
	ds_read_b128 v[210:213], v188 offset:2048
	global_load_lds_dwordx4 v176, s[98:99]
	s_add_i32 m0, s20, 0x1a000
	ds_read_b128 v[214:217], v188 offset:3072
	global_load_lds_dwordx4 v128, s[98:99]
	s_barrier
	s_waitcnt lgkmcnt(3)
	v_mfma_f32_16x16x32_bf16 v[108:111], v[202:205], v[158:161], v[108:111]
	s_waitcnt lgkmcnt(1)
	v_mfma_f32_16x16x32_bf16 v[104:107], v[210:213], v[158:161], v[104:107]
	v_mfma_f32_16x16x32_bf16 v[92:95], v[202:205], v[166:169], v[92:95]
	v_mfma_f32_16x16x32_bf16 v[88:91], v[210:213], v[166:169], v[88:91]
	v_mfma_f32_16x16x32_bf16 v[76:79], v[202:205], v[182:185], v[76:79]
	v_mfma_f32_16x16x32_bf16 v[72:75], v[210:213], v[182:185], v[72:75]
	v_mfma_f32_16x16x32_bf16 v[68:71], v[202:205], v[194:197], v[68:71]
	v_mfma_f32_16x16x32_bf16 v[64:67], v[210:213], v[194:197], v[64:67]
	v_mfma_f32_16x16x32_bf16 v[108:111], v[206:209], v[162:165], v[108:111]
	s_waitcnt lgkmcnt(0)
	v_mfma_f32_16x16x32_bf16 v[104:107], v[214:217], v[162:165], v[104:107]
	v_mfma_f32_16x16x32_bf16 v[92:95], v[206:209], v[170:173], v[92:95]
	v_mfma_f32_16x16x32_bf16 v[88:91], v[214:217], v[170:173], v[88:91]
	v_mfma_f32_16x16x32_bf16 v[76:79], v[206:209], v[190:193], v[76:79]
	v_mfma_f32_16x16x32_bf16 v[72:75], v[214:217], v[190:193], v[72:75]
	v_mfma_f32_16x16x32_bf16 v[68:71], v[206:209], v[198:201], v[68:71]
	v_mfma_f32_16x16x32_bf16 v[64:67], v[214:217], v[198:201], v[64:67]
	s_mov_b32 m0, s28
	s_barrier
	ds_read_b128 v[158:161], v141 offset:49152
	ds_read_b128 v[162:165], v141 offset:50176
	ds_read_b128 v[166:169], v141 offset:51200
	ds_read_b128 v[170:173], v141 offset:52224
	ds_read_b128 v[182:185], v141 offset:53248
	ds_read_b128 v[190:193], v141 offset:54272
	ds_read_b128 v[194:197], v141 offset:55296
	global_load_lds_dwordx4 v132, s[100:101]
	s_mov_b32 m0, s29
	ds_read_b128 v[198:201], v141 offset:56320
	global_load_lds_dwordx4 v130, s[100:101]
	s_barrier
; #define PG8_STAGE(bufoff, gbase, voff) do { _Pragma("unroll") for (int _i = 0; _i < 2; ++_i) \
;         __builtin_amdgcn_global_load_lds((const unsigned*)((const char*)(gbase) + (voff)[_i]), (PG8_LAS unsigned*)(lds + (bufoff) + ldsw + _i * 8192), 16, 0, 0); } while (0)
; #define PG8_MMA(ai, bj, At, Bt) do { __builtin_amdgcn_s_setprio(1); _Pragma("unroll") for (int m = 0; m < 4; ++m) _Pragma("unroll") for (int n = 0; n < 2; ++n) _Pragma("unroll") for (int k = 0; k < 2; ++k) \
;         acc[ai][bj][m][n] = __builtin_amdgcn_mfma_f32_16x16x32_bf16(Bt[n][k], At[m][k], acc[ai][bj][m][n], 0, 0, 0); __builtin_amdgcn_s_setprio(0); } while (0)
; #define PG8_WAIT_V(n) asm volatile("s_waitcnt vmcnt(" #n ")" ::: "memory")
; #define PG8_WAIT_L(n) asm volatile("s_waitcnt lgkmcnt(" #n ")" ::: "memory")
; #define PG8_BAR __builtin_amdgcn_s_barrier()
; #define PG8_SCHED __builtin_amdgcn_sched_barrier(0)
; template <class Epi, class Sched>
; __device__ __forceinline__ void gemm_phase(PG8_LAS unsigned char* lds, const Gemm g, const Sched& S, const Epi& E) {
;     ...
;             PG8_BAR; PG8_WAIT_L(0); PG8_MMA(1, 0, At, B0); PG8_BAR; PG8_SCHED;
;             PG8_STAGE(PG8_SB(1, 1), b3 + hstep, voffB);
;             PG8_WAIT_V(6); PG8_BAR; PG8_MMA(1, 1, At, B1); PG8_BAR;
;         }
	s_waitcnt lgkmcnt(7)
	v_mfma_f32_16x16x32_bf16 v[60:63], v[142:145], v[158:161], v[60:63]
	v_mfma_f32_16x16x32_bf16 v[56:59], v[150:153], v[158:161], v[56:59]
	s_waitcnt lgkmcnt(5)
	v_mfma_f32_16x16x32_bf16 v[52:55], v[142:145], v[166:169], v[52:55]
	v_mfma_f32_16x16x32_bf16 v[48:51], v[150:153], v[166:169], v[48:51]
	s_waitcnt lgkmcnt(3)
	v_mfma_f32_16x16x32_bf16 v[36:39], v[142:145], v[182:185], v[36:39]
	v_mfma_f32_16x16x32_bf16 v[32:35], v[150:153], v[182:185], v[32:35]
	s_waitcnt lgkmcnt(1)
	v_mfma_f32_16x16x32_bf16 v[20:23], v[142:145], v[194:197], v[20:23]
	v_mfma_f32_16x16x32_bf16 v[16:19], v[150:153], v[194:197], v[16:19]
	v_mfma_f32_16x16x32_bf16 v[60:63], v[146:149], v[162:165], v[60:63]
	v_mfma_f32_16x16x32_bf16 v[56:59], v[154:157], v[162:165], v[56:59]
	v_mfma_f32_16x16x32_bf16 v[52:55], v[146:149], v[170:173], v[52:55]
	v_mfma_f32_16x16x32_bf16 v[48:51], v[154:157], v[170:173], v[48:51]
	v_mfma_f32_16x16x32_bf16 v[36:39], v[146:149], v[190:193], v[36:39]
	v_mfma_f32_16x16x32_bf16 v[32:35], v[154:157], v[190:193], v[32:35]
	s_waitcnt lgkmcnt(0)
	v_mfma_f32_16x16x32_bf16 v[20:23], v[146:149], v[198:201], v[20:23]
	v_mfma_f32_16x16x32_bf16 v[16:19], v[154:157], v[198:201], v[16:19]
	s_barrier
	s_add_u32 s14, s14, 0x40080
	s_addc_u32 s15, s15, 0
	s_add_i32 m0, s20, 0x1c000
	s_nop 0
	global_load_lds_dwordx4 v176, s[14:15]
	s_add_i32 m0, s20, 0x1e000
	s_nop 0
	global_load_lds_dwordx4 v128, s[14:15]
	s_waitcnt vmcnt(6)
	s_barrier
	v_mfma_f32_16x16x32_bf16 v[44:47], v[202:205], v[158:161], v[44:47]
	v_mfma_f32_16x16x32_bf16 v[40:43], v[210:213], v[158:161], v[40:43]
	v_mfma_f32_16x16x32_bf16 v[28:31], v[202:205], v[166:169], v[28:31]
	v_mfma_f32_16x16x32_bf16 v[24:27], v[210:213], v[166:169], v[24:27]
	v_mfma_f32_16x16x32_bf16 v[12:15], v[202:205], v[182:185], v[12:15]
	v_mfma_f32_16x16x32_bf16 v[8:11], v[210:213], v[182:185], v[8:11]
	v_mfma_f32_16x16x32_bf16 v[4:7], v[202:205], v[194:197], v[4:7]
	v_mfma_f32_16x16x32_bf16 v[0:3], v[210:213], v[194:197], v[0:3]
	v_mfma_f32_16x16x32_bf16 v[44:47], v[206:209], v[162:165], v[44:47]
	v_mfma_f32_16x16x32_bf16 v[40:43], v[214:217], v[162:165], v[40:43]
	v_mfma_f32_16x16x32_bf16 v[28:31], v[206:209], v[170:173], v[28:31]
	v_mfma_f32_16x16x32_bf16 v[24:27], v[214:217], v[170:173], v[24:27]
	v_mfma_f32_16x16x32_bf16 v[12:15], v[206:209], v[190:193], v[12:15]
	v_mfma_f32_16x16x32_bf16 v[8:11], v[214:217], v[190:193], v[8:11]
	v_mfma_f32_16x16x32_bf16 v[4:7], v[206:209], v[198:201], v[4:7]
	v_mfma_f32_16x16x32_bf16 v[0:3], v[214:217], v[198:201], v[0:3]
	s_add_i32 s45, s45, 2
	s_add_u32 s12, s12, 0x100
	s_addc_u32 s13, s13, 0
	s_add_u32 s43, s43, 0x100
	s_addc_u32 s44, s44, 0
	s_cmp_gt_u32 s45, 13
	s_barrier
	s_cbranch_scc0 .LBB0_358
; __device__ __forceinline__ unsigned cvtpk(float lo, float hi) { const f32x2 v = (f32x2){lo, hi}; const bf16v2 b = __builtin_convertvector(v, bf16v2); return __builtin_bit_cast(unsigned, b); }
;     __device__ __forceinline__ void operator()(const f32x4 (&acc)[2][2][4][2], const pg8::Unit& u, int wr, int wc, int fr, int fq) const {
;         const int row0 = u.pm * 256 + wr * 64 + fr, col0 = u.pn * 256 + wc * 32 + 8 * fq;
; #pragma unroll
;         for (int ai = 0; ai < 2; ++ai)
; #pragma unroll
;             for (int m = 0; m < 4; ++m) { bf16_t* rowp = O + (size_t)(row0 + ai * 128 + m * 16) * ldc + col0;
; #pragma unroll
;                 for (int bj = 0; bj < 2; ++bj) { const f32x4 v0 = acc[ai][bj][m][0], v1 = acc[ai][bj][m][1];
;                     u32x4 w; w.x = cvtpk(v0[0], v0[1]); w.y = cvtpk(v0[2], v0[3]); w.z = cvtpk(v1[0], v1[1]); w.w = cvtpk(v1[2], v1[3]);
;                     *(u32x4*)(rowp + bj * 128) = w; } }
;     }
	v_readlane_b32 s12, v253, 16
	v_lshl_add_u32 v148, s0, 8, v138
	v_lshl_or_b32 v142, s34, 8, v140
	v_readlane_b32 s13, v253, 17
	v_ashrrev_i32_e32 v143, 31, v142
	v_cvt_pk_bf16_f32 v68, v68, v69
	v_mov_b64_e32 v[144:145], s[12:13]
	v_cvt_pk_bf16_f32 v69, v70, v71
	v_cvt_pk_bf16_f32 v70, v64, v65
	v_add_u32_e32 v64, 0x80, v148
	v_mad_i64_i32 v[146:147], s[12:13], v148, s81, v[144:145]
	v_lshlrev_b64 v[142:143], 1, v[142:143]
	v_cvt_pk_bf16_f32 v108, v108, v109
	v_cvt_pk_bf16_f32 v109, v110, v111
	v_cvt_pk_bf16_f32 v110, v104, v105
	v_or_b32_e32 v104, 16, v148
	v_mad_i64_i32 v[64:65], s[12:13], v64, s81, v[144:145]
	v_cvt_pk_bf16_f32 v44, v44, v45
	v_cvt_pk_bf16_f32 v45, v46, v47
	v_cvt_pk_bf16_f32 v46, v40, v41
	v_add_u32_e32 v40, 0x90, v148
	v_lshl_add_u64 v[146:147], v[146:147], 0, v[142:143]
	v_cvt_pk_bf16_f32 v111, v106, v107
	v_mad_i64_i32 v[104:105], s[12:13], v104, s81, v[144:145]
	v_cvt_pk_bf16_f32 v92, v92, v93
	v_cvt_pk_bf16_f32 v93, v94, v95
	v_cvt_pk_bf16_f32 v94, v88, v89
	v_or_b32_e32 v88, 32, v148
	v_lshl_add_u64 v[64:65], v[64:65], 0, v[142:143]
	v_cvt_pk_bf16_f32 v47, v42, v43
	v_mad_i64_i32 v[40:41], s[12:13], v40, s81, v[144:145]
	v_cvt_pk_bf16_f32 v28, v28, v29
	v_cvt_pk_bf16_f32 v29, v30, v31
	v_cvt_pk_bf16_f32 v30, v24, v25
	v_add_u32_e32 v24, 0xa0, v148
	global_store_dwordx4 v[146:147], v[108:111], off offset:256 sc1
	v_cvt_pk_bf16_f32 v95, v90, v91
	v_mad_i64_i32 v[88:89], s[12:13], v88, s81, v[144:145]
	v_lshl_add_u64 v[108:109], v[104:105], 0, v[142:143]
	v_cvt_pk_bf16_f32 v76, v76, v77
	v_cvt_pk_bf16_f32 v77, v78, v79
	v_cvt_pk_bf16_f32 v78, v72, v73
	v_or_b32_e32 v72, 48, v148
	global_store_dwordx4 v[64:65], v[44:47], off offset:256 sc1
	v_cvt_pk_bf16_f32 v31, v26, v27
	v_mad_i64_i32 v[24:25], s[12:13], v24, s81, v[144:145]
	v_lshl_add_u64 v[44:45], v[40:41], 0, v[142:143]
	v_cvt_pk_bf16_f32 v12, v12, v13
	v_cvt_pk_bf16_f32 v13, v14, v15
	v_cvt_pk_bf16_f32 v14, v8, v9
	v_add_u32_e32 v8, 0xb0, v148
	global_store_dwordx4 v[108:109], v[92:95], off offset:256 sc1
	v_cvt_pk_bf16_f32 v79, v74, v75
	v_mad_i64_i32 v[72:73], s[12:13], v72, s81, v[144:145]
	v_lshl_add_u64 v[92:93], v[88:89], 0, v[142:143]
	global_store_dwordx4 v[44:45], v[28:31], off offset:256 sc1
	v_cvt_pk_bf16_f32 v15, v10, v11
	v_mad_i64_i32 v[8:9], s[12:13], v8, s81, v[144:145]
	v_lshl_add_u64 v[28:29], v[24:25], 0, v[142:143]
	v_cvt_pk_bf16_f32 v124, v124, v125
	v_cvt_pk_bf16_f32 v125, v126, v127
	v_cvt_pk_bf16_f32 v126, v120, v121
	v_cvt_pk_bf16_f32 v127, v122, v123
	v_cvt_pk_bf16_f32 v104, v116, v117
	v_cvt_pk_bf16_f32 v105, v118, v119
	v_cvt_pk_bf16_f32 v106, v112, v113
	v_cvt_pk_bf16_f32 v107, v114, v115
	v_cvt_pk_bf16_f32 v88, v100, v101
	v_cvt_pk_bf16_f32 v89, v102, v103
	v_cvt_pk_bf16_f32 v90, v96, v97
	v_cvt_pk_bf16_f32 v91, v98, v99
	global_store_dwordx4 v[92:93], v[76:79], off offset:256 sc1
	v_cvt_pk_bf16_f32 v74, v80, v81
	v_cvt_pk_bf16_f32 v75, v82, v83
	v_lshl_add_u64 v[76:77], v[72:73], 0, v[142:143]
	v_cvt_pk_bf16_f32 v72, v84, v85
	v_cvt_pk_bf16_f32 v73, v86, v87
	v_cvt_pk_bf16_f32 v71, v66, v67
	v_cvt_pk_bf16_f32 v60, v60, v61
	v_cvt_pk_bf16_f32 v61, v62, v63
	v_cvt_pk_bf16_f32 v62, v56, v57
	v_cvt_pk_bf16_f32 v63, v58, v59
	v_cvt_pk_bf16_f32 v40, v52, v53
	v_cvt_pk_bf16_f32 v41, v54, v55
	v_cvt_pk_bf16_f32 v42, v48, v49
	v_cvt_pk_bf16_f32 v43, v50, v51
	v_cvt_pk_bf16_f32 v24, v36, v37
	v_cvt_pk_bf16_f32 v25, v38, v39
	v_cvt_pk_bf16_f32 v26, v32, v33
	v_cvt_pk_bf16_f32 v27, v34, v35
	global_store_dwordx4 v[28:29], v[12:15], off offset:256 sc1
	v_cvt_pk_bf16_f32 v10, v16, v17
	v_cvt_pk_bf16_f32 v11, v18, v19
	v_lshl_add_u64 v[12:13], v[8:9], 0, v[142:143]
	v_cvt_pk_bf16_f32 v8, v20, v21
	v_cvt_pk_bf16_f32 v9, v22, v23
	v_cvt_pk_bf16_f32 v4, v4, v5
	v_cvt_pk_bf16_f32 v5, v6, v7
	v_cvt_pk_bf16_f32 v6, v0, v1
	v_cvt_pk_bf16_f32 v7, v2, v3
	s_and_b64 vcc, exec, s[38:39]
	s_mov_b32 s34, s4
	s_mov_b32 s0, s6
	s_mov_b64 s[14:15], s[10:11]
	s_mov_b64 s[12:13], s[8:9]
	global_store_dwordx4 v[146:147], v[124:127], off sc1
	global_store_dwordx4 v[108:109], v[104:107], off sc1
	global_store_dwordx4 v[92:93], v[88:91], off sc1
	global_store_dwordx4 v[76:77], v[72:75], off sc1
	global_store_dwordx4 v[76:77], v[68:71], off offset:256 sc1
	global_store_dwordx4 v[64:65], v[60:63], off sc1
	global_store_dwordx4 v[44:45], v[40:43], off sc1
	global_store_dwordx4 v[28:29], v[24:27], off sc1
	global_store_dwordx4 v[12:13], v[8:11], off sc1
	global_store_dwordx4 v[12:13], v[4:7], off offset:256 sc1
	s_cbranch_vccz .LBB0_355
	s_waitcnt vmcnt(0)
	v_readlane_b32 s22, v255, 14
	s_cmpk_gt_u32 s19, 0xff
	v_readlane_b32 s23, v255, 15
	s_mov_b64 s[28:29], s[54:55]
	s_cbranch_scc1 .LBB0_362
	s_barrier

; __device__ __forceinline__ unsigned cvtpk(float lo, float hi) { const f32x2 v = (f32x2){lo, hi}; const bf16v2 b = __builtin_convertvector(v, bf16v2); return __builtin_bit_cast(unsigned, b); }
; __device__ void phase_rowprep(const float* xsrc, const bf16_t* __restrict__ m, const float* __restrict__ gpost, float* xdst, const float* __restrict__ gpre, bf16_t* __restrict__ hdst) {
;     ...
;         if (hdst) {
;             float ss = 0.f;
; #pragma unroll
;             for (int i = 0; i < 4; ++i) ss += xv[i][0] * xv[i][0] + xv[i][1] * xv[i][1] + xv[i][2] * xv[i][2] + xv[i][3] * xv[i][3];
; #pragma unroll
;             for (int o = 32; o >= 1; o >>= 1) ss += __shfl_xor(ss, o);
;             const float rs = rsqrtf(ss * (1.0f / D) + EPS);
; #pragma unroll
;             for (int i = 0; i < 4; ++i) { const f32x4 hv = xv[i] * rs * gq[i]; *(u32x2*)(hdst + (size_t)row * D + i * 256 + lane * 4) = (u32x2){cvtpk(hv[0], hv[1]), cvtpk(hv[2], hv[3])}; }
;         }
;         row = nrow;
.LBB0_547:
	v_mov_b32_e32 v86, v61
	v_mov_b32_e32 v87, v57
	v_mov_b32_e32 v84, v60
	v_mov_b32_e32 v85, v56
	v_pk_mul_f32 v[86:87], v[86:87], v[86:87]
	v_mov_b32_e32 v88, v49
	v_pk_fma_f32 v[84:85], v[84:85], v[84:85], v[86:87]
	v_mov_b32_e32 v86, v62
	v_mov_b32_e32 v87, v58
	v_pk_fma_f32 v[84:85], v[86:87], v[86:87], v[84:85]
	v_mov_b32_e32 v86, v63
	v_mov_b32_e32 v87, v59
	v_mov_b32_e32 v89, v53
	v_pk_fma_f32 v[84:85], v[86:87], v[86:87], v[84:85]
	v_mov_b32_e32 v86, v48
	v_mov_b32_e32 v87, v52
	v_pk_mul_f32 v[88:89], v[88:89], v[88:89]
	v_add_f32_e32 v84, v84, v85
	v_pk_fma_f32 v[86:87], v[86:87], v[86:87], v[88:89]
	v_mov_b32_e32 v88, v50
	v_mov_b32_e32 v89, v54
	v_pk_fma_f32 v[86:87], v[88:89], v[88:89], v[86:87]
	v_mov_b32_e32 v88, v51
	v_mov_b32_e32 v89, v55
	v_pk_fma_f32 v[86:87], v[88:89], v[88:89], v[86:87]
	s_and_b64 s[0:1], exec, s[0:1]
	v_add_f32_e32 v84, v87, v84
	v_add_f32_e32 v84, v86, v84
	ds_bpermute_b32 v85, v65, v84
	s_or_b64 s[6:7], s[0:1], s[6:7]
	v_lshl_add_u64 v[66:67], v[66:67], 0, s[12:13]
	v_lshl_add_u64 v[72:73], v[72:73], 0, s[12:13]
	v_lshl_add_u64 v[74:75], v[74:75], 0, s[10:11]
	s_waitcnt lgkmcnt(0)
	v_add_f32_e32 v84, v84, v85
	ds_bpermute_b32 v85, v92, v84
	s_waitcnt vmcnt(3)
	v_mov_b64_e32 v[90:91], v[76:77]
	s_waitcnt vmcnt(2)
	v_mov_b64_e32 v[88:89], v[78:79]
	s_waitcnt lgkmcnt(0)
	v_add_f32_e32 v84, v84, v85
	ds_bpermute_b32 v85, v93, v84
	s_waitcnt lgkmcnt(0)
	v_add_f32_e32 v84, v84, v85
	ds_bpermute_b32 v85, v94, v84
	s_waitcnt lgkmcnt(0)
	v_add_f32_e32 v84, v84, v85
	ds_bpermute_b32 v85, v95, v84
	s_waitcnt lgkmcnt(0)
	v_add_f32_e32 v84, v84, v85
	ds_bpermute_b32 v85, v96, v84
	s_waitcnt lgkmcnt(0)
	v_add_f32_e32 v84, v84, v85
	v_fmamk_f32 v84, v84, 0x3a800000, v225
	v_mul_f32_e32 v85, 0x4b800000, v84
	v_cmp_gt_f32_e32 vcc, s25, v84
	s_nop 1
	v_cndmask_b32_e32 v84, v84, v85, vcc
	v_rsq_f32_e32 v86, v84
	v_lshl_add_u64 v[84:85], v[70:71], 0, v[176:177]
	v_lshl_add_u64 v[70:71], v[70:71], 0, s[10:11]
	v_mul_f32_e32 v87, 0x45800000, v86
	v_cndmask_b32_e32 v86, v86, v87, vcc
	v_pk_mul_f32 v[60:61], v[60:61], v[86:87] op_sel_hi:[1,0]
	v_pk_mul_f32 v[62:63], v[62:63], v[86:87] op_sel_hi:[1,0]
	v_pk_mul_f32 v[60:61], v[8:9], v[60:61]
	v_pk_mul_f32 v[62:63], v[10:11], v[62:63]
	v_pk_mul_f32 v[56:57], v[56:57], v[86:87] op_sel_hi:[1,0]
	v_pk_mul_f32 v[58:59], v[58:59], v[86:87] op_sel_hi:[1,0]
	v_pk_mul_f32 v[52:53], v[52:53], v[86:87] op_sel_hi:[1,0]
	v_pk_mul_f32 v[54:55], v[54:55], v[86:87] op_sel_hi:[1,0]
	v_pk_mul_f32 v[48:49], v[48:49], v[86:87] op_sel_hi:[1,0]
	v_pk_mul_f32 v[50:51], v[50:51], v[86:87] op_sel_hi:[1,0]
	v_cvt_pk_bf16_f32 v60, v60, v61
	v_cvt_pk_bf16_f32 v61, v62, v63
	v_add_co_u32_e32 v62, vcc, s83, v84
	v_pk_mul_f32 v[58:59], v[14:15], v[58:59]
	v_pk_mul_f32 v[56:57], v[12:13], v[56:57]
	v_pk_mul_f32 v[54:55], v[26:27], v[54:55]
	v_pk_mul_f32 v[52:53], v[24:25], v[52:53]
	v_pk_mul_f32 v[50:51], v[30:31], v[50:51]
	v_pk_mul_f32 v[48:49], v[28:29], v[48:49]
	v_addc_co_u32_e32 v63, vcc, 0, v85, vcc
	v_cvt_pk_bf16_f32 v56, v56, v57
	v_cvt_pk_bf16_f32 v57, v58, v59
	v_cvt_pk_bf16_f32 v52, v52, v53
	v_cvt_pk_bf16_f32 v53, v54, v55
	v_cvt_pk_bf16_f32 v48, v48, v49
	v_cvt_pk_bf16_f32 v49, v50, v51
	global_store_dwordx2 v[62:63], v[60:61], off sc1
	global_store_dwordx2 v[62:63], v[56:57], off offset:512 sc1
	global_store_dwordx2 v[62:63], v[52:53], off offset:1024 sc1
	global_store_dwordx2 v[62:63], v[48:49], off offset:1536 sc1
	v_mov_b64_e32 v[62:63], v[34:35]
	v_mov_b64_e32 v[58:59], v[38:39]
	v_mov_b64_e32 v[54:55], v[42:43]
	v_mov_b64_e32 v[50:51], v[46:47]
	s_waitcnt vmcnt(5)
	v_mov_b64_e32 v[86:87], v[80:81]
	s_waitcnt vmcnt(4)
	v_mov_b64_e32 v[84:85], v[82:83]
	v_mov_b64_e32 v[60:61], v[32:33]
	v_mov_b64_e32 v[56:57], v[36:37]
	v_mov_b64_e32 v[52:53], v[40:41]
	v_mov_b64_e32 v[48:49], v[44:45]
	s_andn2_b64 exec, exec, s[6:7]
	s_cbranch_execz .LBB0_552
